# down2 DPP redistribution reordered for ILP (independent DPP adds grouped, selects last)
# speedup vs baseline: 1.0049x; 1.0032x over previous
; DI float bflo(u32 u) { return __uint_as_float(u << 16); }
; DI float bfhi(u32 u) { return __uint_as_float(u & 0xffff0000u); }
; DI void dn2_math(const u32x4 (&W)[16], u32x4 x0, u32x4 x1, float* __restrict__ parow, int lane) {
;   f2 xf[8];
; #pragma unroll
;   for (int q = 0; q < 4; ++q) { xf[q] = f2{bflo(x0[q]), bfhi(x0[q])}; xf[4 + q] = f2{bflo(x1[q]), bfhi(x1[q])}; }
;   float pv[16];
; #pragma unroll
;   for (int j = 0; j < 16; ++j) {
;     f2 s2 = {0.f, 0.f};
; #pragma unroll
;     for (int d = 0; d < 4; ++d) {
;       f2 lo = __builtin_amdgcn_cvt_pk_f32_fp8((int)W[j][d], false);
;       f2 hi = __builtin_amdgcn_cvt_pk_f32_fp8((int)W[j][d], true);
;       s2 = lo * xf[2 * d] + s2;
;       s2 = hi * xf[2 * d + 1] + s2;
;     }
;     pv[j] = s2.x + s2.y;
; DI void peer_down2_phase(const Params& p, unsigned char* smem, int layer, const bf16* __restrict__ x1b, u32* ctr) {
;     ...
;       for (int tl = 0; tl < 16; tl += 2) {
;         dn2_issue(WB, pl + (tl + 1) * 128, wbase, grp);
.LBB0_693:
	s_add_i32 s46, s46, 2
	s_waitcnt vmcnt(19)
	v_cvt_pk_f32_fp8_e32 v[210:211], v134
	v_cvt_pk_f32_fp8_sdwa v[212:213], v134 src0_sel:WORD_1
	v_cvt_pk_f32_fp8_e32 v[214:215], v135
	s_waitcnt vmcnt(2)
	v_lshlrev_b32_e32 v204, 16, v142
	v_and_b32_e32 v205, 0xffff0000, v142
	v_cvt_pk_f32_fp8_sdwa v[134:135], v135 src0_sel:WORD_1
	v_lshlrev_b32_e32 v206, 16, v143
	v_and_b32_e32 v207, 0xffff0000, v143
	v_pk_fma_f32 v[210:211], v[210:211], v[204:205], 0 op_sel_hi:[1,1,0]
	v_lshlrev_b32_e32 v208, 16, v144
	v_and_b32_e32 v209, 0xffff0000, v144
	v_pk_fma_f32 v[210:211], v[212:213], v[206:207], v[210:211]
	v_lshlrev_b32_e32 v144, 16, v145
	v_and_b32_e32 v145, 0xffff0000, v145
	v_pk_fma_f32 v[210:211], v[214:215], v[208:209], v[210:211]
	v_cvt_pk_f32_fp8_sdwa v[212:213], v136 src0_sel:WORD_1
	v_pk_fma_f32 v[134:135], v[134:135], v[144:145], v[210:211]
	v_cvt_pk_f32_fp8_e32 v[210:211], v136
	v_cvt_pk_f32_fp8_e32 v[214:215], v137
	v_lshlrev_b32_e32 v202, 16, v138
	v_and_b32_e32 v203, 0xffff0000, v138
	v_cvt_pk_f32_fp8_sdwa v[136:137], v137 src0_sel:WORD_1
	v_lshlrev_b32_e32 v138, 16, v139
	v_and_b32_e32 v139, 0xffff0000, v139
	v_pk_fma_f32 v[134:135], v[210:211], v[202:203], v[134:135]
	v_lshlrev_b32_e32 v142, 16, v140
	v_and_b32_e32 v143, 0xffff0000, v140
	v_pk_fma_f32 v[134:135], v[212:213], v[138:139], v[134:135]
	v_lshlrev_b32_e32 v140, 16, v141
	v_and_b32_e32 v141, 0xffff0000, v141
	v_pk_fma_f32 v[134:135], v[214:215], v[142:143], v[134:135]
	v_cvt_pk_f32_fp8_e32 v[210:211], v131
	v_pk_fma_f32 v[134:135], v[136:137], v[140:141], v[134:135]
	v_cvt_pk_f32_fp8_sdwa v[136:137], v130 src0_sel:WORD_1
	v_add_f32_e32 v167, v134, v135
	v_cvt_pk_f32_fp8_e32 v[134:135], v130
	v_cvt_pk_f32_fp8_sdwa v[130:131], v131 src0_sel:WORD_1
	v_pk_fma_f32 v[134:135], v[134:135], v[204:205], 0 op_sel_hi:[1,1,0]
	s_nop 0
	v_pk_fma_f32 v[134:135], v[136:137], v[206:207], v[134:135]
	v_cvt_pk_f32_fp8_sdwa v[136:137], v132 src0_sel:WORD_1
	v_pk_fma_f32 v[134:135], v[210:211], v[208:209], v[134:135]
	v_cvt_pk_f32_fp8_e32 v[210:211], v133
	v_pk_fma_f32 v[130:131], v[130:131], v[144:145], v[134:135]
	v_cvt_pk_f32_fp8_e32 v[134:135], v132
	v_cvt_pk_f32_fp8_sdwa v[132:133], v133 src0_sel:WORD_1
	v_pk_fma_f32 v[130:131], v[134:135], v[202:203], v[130:131]
	s_nop 0
	v_pk_fma_f32 v[130:131], v[136:137], v[138:139], v[130:131]
	v_cvt_pk_f32_fp8_e32 v[134:135], v127
	v_pk_fma_f32 v[130:131], v[210:211], v[142:143], v[130:131]
	s_nop 0
	v_pk_fma_f32 v[130:131], v[132:133], v[140:141], v[130:131]
	v_cvt_pk_f32_fp8_sdwa v[132:133], v126 src0_sel:WORD_1
	v_add_f32_e32 v136, v130, v131
	v_cvt_pk_f32_fp8_e32 v[130:131], v126
	v_cvt_pk_f32_fp8_sdwa v[126:127], v127 src0_sel:WORD_1
	v_pk_fma_f32 v[130:131], v[130:131], v[204:205], 0 op_sel_hi:[1,1,0]
	s_nop 0
	v_pk_fma_f32 v[130:131], v[132:133], v[206:207], v[130:131]
	v_cvt_pk_f32_fp8_sdwa v[132:133], v128 src0_sel:WORD_1
	v_pk_fma_f32 v[130:131], v[134:135], v[208:209], v[130:131]
	v_cvt_pk_f32_fp8_e32 v[134:135], v129
	v_pk_fma_f32 v[126:127], v[126:127], v[144:145], v[130:131]
	v_cvt_pk_f32_fp8_e32 v[130:131], v128
	v_cvt_pk_f32_fp8_sdwa v[128:129], v129 src0_sel:WORD_1
	v_pk_fma_f32 v[126:127], v[130:131], v[202:203], v[126:127]
	s_nop 0
	v_pk_fma_f32 v[126:127], v[132:133], v[138:139], v[126:127]
	v_cvt_pk_f32_fp8_e32 v[130:131], v123
	v_pk_fma_f32 v[126:127], v[134:135], v[142:143], v[126:127]
	s_nop 0
	v_pk_fma_f32 v[126:127], v[128:129], v[140:141], v[126:127]
	v_cvt_pk_f32_fp8_sdwa v[128:129], v122 src0_sel:WORD_1
	v_add_f32_e32 v132, v126, v127
	v_cvt_pk_f32_fp8_e32 v[126:127], v122
	v_cvt_pk_f32_fp8_sdwa v[122:123], v123 src0_sel:WORD_1
	v_pk_fma_f32 v[126:127], v[126:127], v[204:205], 0 op_sel_hi:[1,1,0]
	s_nop 0
	v_pk_fma_f32 v[126:127], v[128:129], v[206:207], v[126:127]
	v_cvt_pk_f32_fp8_sdwa v[128:129], v124 src0_sel:WORD_1
	v_pk_fma_f32 v[126:127], v[130:131], v[208:209], v[126:127]
	v_cvt_pk_f32_fp8_e32 v[130:131], v125
	v_pk_fma_f32 v[122:123], v[122:123], v[144:145], v[126:127]
	v_cvt_pk_f32_fp8_e32 v[126:127], v124
	v_cvt_pk_f32_fp8_sdwa v[124:125], v125 src0_sel:WORD_1
	v_pk_fma_f32 v[122:123], v[126:127], v[202:203], v[122:123]
	s_nop 0
	v_pk_fma_f32 v[122:123], v[128:129], v[138:139], v[122:123]
	v_cvt_pk_f32_fp8_e32 v[126:127], v119
	v_pk_fma_f32 v[122:123], v[130:131], v[142:143], v[122:123]
	s_nop 0
	v_pk_fma_f32 v[122:123], v[124:125], v[140:141], v[122:123]
	v_cvt_pk_f32_fp8_sdwa v[124:125], v118 src0_sel:WORD_1
	v_add_f32_e32 v128, v122, v123
	v_cvt_pk_f32_fp8_e32 v[122:123], v118
	v_cvt_pk_f32_fp8_sdwa v[118:119], v119 src0_sel:WORD_1
	v_pk_fma_f32 v[122:123], v[122:123], v[204:205], 0 op_sel_hi:[1,1,0]
	s_nop 0
	v_pk_fma_f32 v[122:123], v[124:125], v[206:207], v[122:123]
	v_cvt_pk_f32_fp8_sdwa v[124:125], v120 src0_sel:WORD_1
	v_pk_fma_f32 v[122:123], v[126:127], v[208:209], v[122:123]
	v_cvt_pk_f32_fp8_e32 v[126:127], v121
	v_pk_fma_f32 v[118:119], v[118:119], v[144:145], v[122:123]
	v_cvt_pk_f32_fp8_e32 v[122:123], v120
	v_cvt_pk_f32_fp8_sdwa v[120:121], v121 src0_sel:WORD_1
	v_pk_fma_f32 v[118:119], v[122:123], v[202:203], v[118:119]
	s_nop 0
	v_pk_fma_f32 v[118:119], v[124:125], v[138:139], v[118:119]
	v_cvt_pk_f32_fp8_e32 v[122:123], v115
	v_pk_fma_f32 v[118:119], v[126:127], v[142:143], v[118:119]
	s_nop 0
	v_pk_fma_f32 v[118:119], v[120:121], v[140:141], v[118:119]
	v_cvt_pk_f32_fp8_sdwa v[120:121], v114 src0_sel:WORD_1
	v_add_f32_e32 v124, v118, v119
	v_cvt_pk_f32_fp8_e32 v[118:119], v114
	v_cvt_pk_f32_fp8_sdwa v[114:115], v115 src0_sel:WORD_1
	v_pk_fma_f32 v[118:119], v[118:119], v[204:205], 0 op_sel_hi:[1,1,0]
	s_nop 0
	v_pk_fma_f32 v[118:119], v[120:121], v[206:207], v[118:119]
; DI void dn2_math(const u32x4 (&W)[16], u32x4 x0, u32x4 x1, float* __restrict__ parow, int lane) {
;     ...
;   for (int j = 0; j < 16; ++j) {
;     f2 s2 = {0.f, 0.f};
; #pragma unroll
;     for (int d = 0; d < 4; ++d) {
;       f2 lo = __builtin_amdgcn_cvt_pk_f32_fp8((int)W[j][d], false);
;       f2 hi = __builtin_amdgcn_cvt_pk_f32_fp8((int)W[j][d], true);
;       s2 = lo * xf[2 * d] + s2;
;       s2 = hi * xf[2 * d + 1] + s2;
;     }
;     pv[j] = s2.x + s2.y;
	v_cvt_pk_f32_fp8_sdwa v[120:121], v116 src0_sel:WORD_1
	v_pk_fma_f32 v[118:119], v[122:123], v[208:209], v[118:119]
	v_cvt_pk_f32_fp8_e32 v[122:123], v117
	v_pk_fma_f32 v[114:115], v[114:115], v[144:145], v[118:119]
	v_cvt_pk_f32_fp8_e32 v[118:119], v116
	v_cvt_pk_f32_fp8_sdwa v[116:117], v117 src0_sel:WORD_1
	v_pk_fma_f32 v[114:115], v[118:119], v[202:203], v[114:115]
	s_nop 0
	v_pk_fma_f32 v[114:115], v[120:121], v[138:139], v[114:115]
	v_cvt_pk_f32_fp8_e32 v[118:119], v111
	v_pk_fma_f32 v[114:115], v[122:123], v[142:143], v[114:115]
	s_nop 0
	v_pk_fma_f32 v[114:115], v[116:117], v[140:141], v[114:115]
	v_cvt_pk_f32_fp8_sdwa v[116:117], v110 src0_sel:WORD_1
	v_add_f32_e32 v120, v114, v115
	v_cvt_pk_f32_fp8_e32 v[114:115], v110
	v_cvt_pk_f32_fp8_sdwa v[110:111], v111 src0_sel:WORD_1
	v_pk_fma_f32 v[114:115], v[114:115], v[204:205], 0 op_sel_hi:[1,1,0]
	s_nop 0
	v_pk_fma_f32 v[114:115], v[116:117], v[206:207], v[114:115]
	v_cvt_pk_f32_fp8_sdwa v[116:117], v112 src0_sel:WORD_1
	v_pk_fma_f32 v[114:115], v[118:119], v[208:209], v[114:115]
	v_cvt_pk_f32_fp8_e32 v[118:119], v113
	v_pk_fma_f32 v[110:111], v[110:111], v[144:145], v[114:115]
	v_cvt_pk_f32_fp8_e32 v[114:115], v112
	v_cvt_pk_f32_fp8_sdwa v[112:113], v113 src0_sel:WORD_1
	v_pk_fma_f32 v[110:111], v[114:115], v[202:203], v[110:111]
	s_nop 0
	v_pk_fma_f32 v[110:111], v[116:117], v[138:139], v[110:111]
	v_cvt_pk_f32_fp8_e32 v[114:115], v107
	v_pk_fma_f32 v[110:111], v[118:119], v[142:143], v[110:111]
	s_nop 0
	v_pk_fma_f32 v[110:111], v[112:113], v[140:141], v[110:111]
	v_cvt_pk_f32_fp8_sdwa v[112:113], v106 src0_sel:WORD_1
	v_add_f32_e32 v116, v110, v111
	v_cvt_pk_f32_fp8_e32 v[110:111], v106
	v_cvt_pk_f32_fp8_sdwa v[106:107], v107 src0_sel:WORD_1
	v_pk_fma_f32 v[110:111], v[110:111], v[204:205], 0 op_sel_hi:[1,1,0]
	s_nop 0
	v_pk_fma_f32 v[110:111], v[112:113], v[206:207], v[110:111]
	v_cvt_pk_f32_fp8_sdwa v[112:113], v108 src0_sel:WORD_1
	v_pk_fma_f32 v[110:111], v[114:115], v[208:209], v[110:111]
	v_cvt_pk_f32_fp8_e32 v[114:115], v109
	v_pk_fma_f32 v[106:107], v[106:107], v[144:145], v[110:111]
	v_cvt_pk_f32_fp8_e32 v[110:111], v108
	v_cvt_pk_f32_fp8_sdwa v[108:109], v109 src0_sel:WORD_1
	v_pk_fma_f32 v[106:107], v[110:111], v[202:203], v[106:107]
	s_nop 0
	v_pk_fma_f32 v[106:107], v[112:113], v[138:139], v[106:107]
	v_cvt_pk_f32_fp8_e32 v[110:111], v103
	v_pk_fma_f32 v[106:107], v[114:115], v[142:143], v[106:107]
	s_nop 0
	v_pk_fma_f32 v[106:107], v[108:109], v[140:141], v[106:107]
	v_cvt_pk_f32_fp8_sdwa v[108:109], v102 src0_sel:WORD_1
	v_add_f32_e32 v112, v106, v107
	v_cvt_pk_f32_fp8_e32 v[106:107], v102
	v_cvt_pk_f32_fp8_sdwa v[102:103], v103 src0_sel:WORD_1
	v_pk_fma_f32 v[106:107], v[106:107], v[204:205], 0 op_sel_hi:[1,1,0]
	s_nop 0
	v_pk_fma_f32 v[106:107], v[108:109], v[206:207], v[106:107]
	v_cvt_pk_f32_fp8_sdwa v[108:109], v104 src0_sel:WORD_1
	v_pk_fma_f32 v[106:107], v[110:111], v[208:209], v[106:107]
	v_cvt_pk_f32_fp8_e32 v[110:111], v105
	v_pk_fma_f32 v[102:103], v[102:103], v[144:145], v[106:107]
	v_cvt_pk_f32_fp8_e32 v[106:107], v104
	v_cvt_pk_f32_fp8_sdwa v[104:105], v105 src0_sel:WORD_1
	v_pk_fma_f32 v[102:103], v[106:107], v[202:203], v[102:103]
	s_nop 0
	v_pk_fma_f32 v[102:103], v[108:109], v[138:139], v[102:103]
	v_cvt_pk_f32_fp8_e32 v[106:107], v99
	v_pk_fma_f32 v[102:103], v[110:111], v[142:143], v[102:103]
	s_nop 0
	v_pk_fma_f32 v[102:103], v[104:105], v[140:141], v[102:103]
	v_cvt_pk_f32_fp8_sdwa v[104:105], v98 src0_sel:WORD_1
	v_add_f32_e32 v108, v102, v103
	v_cvt_pk_f32_fp8_e32 v[102:103], v98
	v_cvt_pk_f32_fp8_sdwa v[98:99], v99 src0_sel:WORD_1
	v_pk_fma_f32 v[102:103], v[102:103], v[204:205], 0 op_sel_hi:[1,1,0]
	s_nop 0
	v_pk_fma_f32 v[102:103], v[104:105], v[206:207], v[102:103]
	v_cvt_pk_f32_fp8_sdwa v[104:105], v100 src0_sel:WORD_1
	v_pk_fma_f32 v[102:103], v[106:107], v[208:209], v[102:103]
	v_cvt_pk_f32_fp8_e32 v[106:107], v101
	v_pk_fma_f32 v[98:99], v[98:99], v[144:145], v[102:103]
	v_cvt_pk_f32_fp8_e32 v[102:103], v100
	v_cvt_pk_f32_fp8_sdwa v[100:101], v101 src0_sel:WORD_1
	v_pk_fma_f32 v[98:99], v[102:103], v[202:203], v[98:99]
	s_nop 0
	v_pk_fma_f32 v[98:99], v[104:105], v[138:139], v[98:99]
	v_cvt_pk_f32_fp8_e32 v[102:103], v95
	v_pk_fma_f32 v[98:99], v[106:107], v[142:143], v[98:99]
	s_nop 0
	v_pk_fma_f32 v[98:99], v[100:101], v[140:141], v[98:99]
	v_cvt_pk_f32_fp8_sdwa v[100:101], v94 src0_sel:WORD_1
	v_add_f32_e32 v104, v98, v99
	v_cvt_pk_f32_fp8_e32 v[98:99], v94
	v_cvt_pk_f32_fp8_sdwa v[94:95], v95 src0_sel:WORD_1
	v_pk_fma_f32 v[98:99], v[98:99], v[204:205], 0 op_sel_hi:[1,1,0]
	s_nop 0
	v_pk_fma_f32 v[98:99], v[100:101], v[206:207], v[98:99]
	v_cvt_pk_f32_fp8_sdwa v[100:101], v96 src0_sel:WORD_1
	v_pk_fma_f32 v[98:99], v[102:103], v[208:209], v[98:99]
	v_cvt_pk_f32_fp8_e32 v[102:103], v97
	v_pk_fma_f32 v[94:95], v[94:95], v[144:145], v[98:99]
	v_cvt_pk_f32_fp8_e32 v[98:99], v96
	v_cvt_pk_f32_fp8_sdwa v[96:97], v97 src0_sel:WORD_1
	v_pk_fma_f32 v[94:95], v[98:99], v[202:203], v[94:95]
	s_nop 0
	v_pk_fma_f32 v[94:95], v[100:101], v[138:139], v[94:95]
	v_cvt_pk_f32_fp8_e32 v[98:99], v91
	v_pk_fma_f32 v[94:95], v[102:103], v[142:143], v[94:95]
	s_nop 0
	v_pk_fma_f32 v[94:95], v[96:97], v[140:141], v[94:95]
	v_cvt_pk_f32_fp8_sdwa v[96:97], v90 src0_sel:WORD_1
	v_add_f32_e32 v100, v94, v95
	v_cvt_pk_f32_fp8_e32 v[94:95], v90
	v_cvt_pk_f32_fp8_sdwa v[90:91], v91 src0_sel:WORD_1
	v_pk_fma_f32 v[94:95], v[94:95], v[204:205], 0 op_sel_hi:[1,1,0]
	s_nop 0
	v_pk_fma_f32 v[94:95], v[96:97], v[206:207], v[94:95]
	v_cvt_pk_f32_fp8_sdwa v[96:97], v92 src0_sel:WORD_1
	v_pk_fma_f32 v[94:95], v[98:99], v[208:209], v[94:95]
	v_cvt_pk_f32_fp8_e32 v[98:99], v93
; DI void dn2_math(const u32x4 (&W)[16], u32x4 x0, u32x4 x1, float* __restrict__ parow, int lane) {
;     ...
;   for (int j = 0; j < 16; ++j) {
;     f2 s2 = {0.f, 0.f};
; #pragma unroll
;     for (int d = 0; d < 4; ++d) {
;       f2 lo = __builtin_amdgcn_cvt_pk_f32_fp8((int)W[j][d], false);
;       f2 hi = __builtin_amdgcn_cvt_pk_f32_fp8((int)W[j][d], true);
;       s2 = lo * xf[2 * d] + s2;
;       s2 = hi * xf[2 * d + 1] + s2;
;     }
;     pv[j] = s2.x + s2.y;
;   }
;   const bool b2 = lane & 4, b1 = lane & 2, b0 = lane & 1;
;   float q8[8];
; #pragma unroll
;   for (int i = 0; i < 8; ++i) { float snd = b2 ? pv[i] : pv[i + 8]; float kp = b2 ? pv[i + 8] : pv[i]; q8[i] = kp + __shfl_xor(snd, 4); }
;   float q4[4];
; #pragma unroll
;   for (int i = 0; i < 4; ++i) { float snd = b1 ? q8[i] : q8[i + 4]; float kp = b1 ? q8[i + 4] : q8[i]; q4[i] = kp + __shfl_xor(snd, 2); }
;   float r2[2];
; #pragma unroll
;   for (int i = 0; i < 2; ++i) { float snd = b0 ? q4[i] : q4[i + 2]; float kp = b0 ? q4[i + 2] : q4[i]; r2[i] = kp + __shfl_xor(snd, 1); }
;   const int j0 = (b0 ? 2 : 0) + (b1 ? 4 : 0) + (b2 ? 8 : 0);
;   const int grp = lane >> 3;
;   parow[8 * j0 + grp] = r2[0];
;   parow[8 * (j0 + 1) + grp] = r2[1];
	v_pk_fma_f32 v[90:91], v[90:91], v[144:145], v[94:95]
	v_cvt_pk_f32_fp8_e32 v[94:95], v92
	v_cvt_pk_f32_fp8_sdwa v[92:93], v93 src0_sel:WORD_1
	v_pk_fma_f32 v[90:91], v[94:95], v[202:203], v[90:91]
	s_nop 0
	v_pk_fma_f32 v[90:91], v[96:97], v[138:139], v[90:91]
	v_cvt_pk_f32_fp8_e32 v[94:95], v87
	v_pk_fma_f32 v[90:91], v[98:99], v[142:143], v[90:91]
	s_nop 0
	v_pk_fma_f32 v[90:91], v[92:93], v[140:141], v[90:91]
	v_cvt_pk_f32_fp8_sdwa v[92:93], v86 src0_sel:WORD_1
	v_add_f32_e32 v96, v90, v91
	v_cvt_pk_f32_fp8_e32 v[90:91], v86
	v_cvt_pk_f32_fp8_sdwa v[86:87], v87 src0_sel:WORD_1
	v_pk_fma_f32 v[90:91], v[90:91], v[204:205], 0 op_sel_hi:[1,1,0]
	s_nop 0
	v_pk_fma_f32 v[90:91], v[92:93], v[206:207], v[90:91]
	v_cvt_pk_f32_fp8_sdwa v[92:93], v88 src0_sel:WORD_1
	v_pk_fma_f32 v[90:91], v[94:95], v[208:209], v[90:91]
	v_cvt_pk_f32_fp8_e32 v[94:95], v89
	v_pk_fma_f32 v[86:87], v[86:87], v[144:145], v[90:91]
	v_cvt_pk_f32_fp8_e32 v[90:91], v88
	v_cvt_pk_f32_fp8_sdwa v[88:89], v89 src0_sel:WORD_1
	v_pk_fma_f32 v[86:87], v[90:91], v[202:203], v[86:87]
	s_nop 0
	v_pk_fma_f32 v[86:87], v[92:93], v[138:139], v[86:87]
	v_cvt_pk_f32_fp8_e32 v[90:91], v83
	v_pk_fma_f32 v[86:87], v[94:95], v[142:143], v[86:87]
	s_nop 0
	v_pk_fma_f32 v[86:87], v[88:89], v[140:141], v[86:87]
	v_cvt_pk_f32_fp8_sdwa v[88:89], v82 src0_sel:WORD_1
	v_add_f32_e32 v92, v86, v87
	v_cvt_pk_f32_fp8_e32 v[86:87], v82
	v_cvt_pk_f32_fp8_sdwa v[82:83], v83 src0_sel:WORD_1
	v_pk_fma_f32 v[86:87], v[86:87], v[204:205], 0 op_sel_hi:[1,1,0]
	s_nop 0
	v_pk_fma_f32 v[86:87], v[88:89], v[206:207], v[86:87]
	v_cvt_pk_f32_fp8_sdwa v[88:89], v84 src0_sel:WORD_1
	v_pk_fma_f32 v[86:87], v[90:91], v[208:209], v[86:87]
	v_cvt_pk_f32_fp8_e32 v[90:91], v85
	v_pk_fma_f32 v[82:83], v[82:83], v[144:145], v[86:87]
	v_cvt_pk_f32_fp8_e32 v[86:87], v84
	v_cvt_pk_f32_fp8_sdwa v[84:85], v85 src0_sel:WORD_1
	v_pk_fma_f32 v[82:83], v[86:87], v[202:203], v[82:83]
	s_nop 0
	v_pk_fma_f32 v[82:83], v[88:89], v[138:139], v[82:83]
	v_cvt_pk_f32_fp8_e32 v[86:87], v79
	v_pk_fma_f32 v[82:83], v[90:91], v[142:143], v[82:83]
	s_nop 0
	v_pk_fma_f32 v[82:83], v[84:85], v[140:141], v[82:83]
	v_cvt_pk_f32_fp8_sdwa v[84:85], v78 src0_sel:WORD_1
	v_add_f32_e32 v88, v82, v83
	v_cvt_pk_f32_fp8_e32 v[82:83], v78
	v_cvt_pk_f32_fp8_sdwa v[78:79], v79 src0_sel:WORD_1
	v_pk_fma_f32 v[82:83], v[82:83], v[204:205], 0 op_sel_hi:[1,1,0]
	s_nop 0
	v_pk_fma_f32 v[82:83], v[84:85], v[206:207], v[82:83]
	v_cvt_pk_f32_fp8_sdwa v[84:85], v80 src0_sel:WORD_1
	v_pk_fma_f32 v[82:83], v[86:87], v[208:209], v[82:83]
	v_cvt_pk_f32_fp8_e32 v[86:87], v81
	v_pk_fma_f32 v[78:79], v[78:79], v[144:145], v[82:83]
	v_cvt_pk_f32_fp8_e32 v[82:83], v80
	v_cvt_pk_f32_fp8_sdwa v[80:81], v81 src0_sel:WORD_1
	v_pk_fma_f32 v[78:79], v[82:83], v[202:203], v[78:79]
	s_nop 0
	v_pk_fma_f32 v[78:79], v[84:85], v[138:139], v[78:79]
	v_cvt_pk_f32_fp8_e32 v[82:83], v75
	v_pk_fma_f32 v[78:79], v[86:87], v[142:143], v[78:79]
	s_nop 0
	v_pk_fma_f32 v[78:79], v[80:81], v[140:141], v[78:79]
	v_cvt_pk_f32_fp8_sdwa v[80:81], v74 src0_sel:WORD_1
	v_add_f32_e32 v84, v78, v79
	v_cvt_pk_f32_fp8_e32 v[78:79], v74
	v_cvt_pk_f32_fp8_sdwa v[74:75], v75 src0_sel:WORD_1
	v_pk_fma_f32 v[78:79], v[78:79], v[204:205], 0 op_sel_hi:[1,1,0]
	s_nop 0
	v_pk_fma_f32 v[78:79], v[80:81], v[206:207], v[78:79]
	v_cvt_pk_f32_fp8_sdwa v[80:81], v76 src0_sel:WORD_1
	v_pk_fma_f32 v[78:79], v[82:83], v[208:209], v[78:79]
	v_cvt_pk_f32_fp8_e32 v[82:83], v77
	v_pk_fma_f32 v[74:75], v[74:75], v[144:145], v[78:79]
	v_cvt_pk_f32_fp8_e32 v[78:79], v76
	v_cvt_pk_f32_fp8_sdwa v[76:77], v77 src0_sel:WORD_1
	v_pk_fma_f32 v[74:75], v[78:79], v[202:203], v[74:75]
	s_nop 0
	v_pk_fma_f32 v[74:75], v[80:81], v[138:139], v[74:75]
	v_pk_fma_f32 v[74:75], v[82:83], v[142:143], v[74:75]
	v_pk_fma_f32 v[74:75], v[76:77], v[140:141], v[74:75]
	v_add_f32_e32 v74, v74, v75
	s_nop 1
	v_add_f32_dpp v74, v74, v74 row_shr:4 row_mask:0xf bank_mask:0xa
	v_add_f32_dpp v75, v167, v167 row_shl:4 row_mask:0xf bank_mask:0x5
	v_add_f32_dpp v76, v136, v136 row_shl:4 row_mask:0xf bank_mask:0x5
	v_add_f32_dpp v77, v132, v132 row_shl:4 row_mask:0xf bank_mask:0x5
	v_add_f32_dpp v78, v128, v128 row_shl:4 row_mask:0xf bank_mask:0x5
	v_add_f32_dpp v79, v124, v124 row_shl:4 row_mask:0xf bank_mask:0x5
	v_add_f32_dpp v80, v120, v120 row_shl:4 row_mask:0xf bank_mask:0x5
	v_add_f32_dpp v81, v116, v116 row_shl:4 row_mask:0xf bank_mask:0x5
	v_add_f32_dpp v74, v112, v112 row_shl:4 row_mask:0xf bank_mask:0x5
	v_add_f32_dpp v75, v108, v108 row_shr:4 row_mask:0xf bank_mask:0xa
	v_add_f32_dpp v76, v104, v104 row_shr:4 row_mask:0xf bank_mask:0xa
	v_add_f32_dpp v77, v100, v100 row_shr:4 row_mask:0xf bank_mask:0xa
	v_add_f32_dpp v78, v96, v96 row_shr:4 row_mask:0xf bank_mask:0xa
	v_add_f32_dpp v79, v92, v92 row_shr:4 row_mask:0xf bank_mask:0xa
	v_add_f32_dpp v80, v88, v88 row_shr:4 row_mask:0xf bank_mask:0xa
	v_add_f32_dpp v81, v84, v84 row_shr:4 row_mask:0xf bank_mask:0xa
	s_nop 1
	v_add_f32_dpp v75, v75, v75 quad_perm:[2,3,0,1] row_mask:0xf bank_mask:0xf
	v_add_f32_dpp v77, v77, v77 quad_perm:[2,3,0,1] row_mask:0xf bank_mask:0xf
	v_add_f32_dpp v76, v76, v76 quad_perm:[2,3,0,1] row_mask:0xf bank_mask:0xf
	v_add_f32_dpp v78, v78, v78 quad_perm:[2,3,0,1] row_mask:0xf bank_mask:0xf
	v_add_f32_dpp v79, v79, v79 quad_perm:[2,3,0,1] row_mask:0xf bank_mask:0xf
	v_add_f32_dpp v81, v81, v81 quad_perm:[2,3,0,1] row_mask:0xf bank_mask:0xf
	v_add_f32_dpp v80, v80, v80 quad_perm:[2,3,0,1] row_mask:0xf bank_mask:0xf
	v_add_f32_dpp v74, v74, v74 quad_perm:[2,3,0,1] row_mask:0xf bank_mask:0xf
	v_cndmask_b32_e64 v75, v79, v75, s[12:13]
	v_cndmask_b32_e64 v77, v81, v77, s[12:13]
	v_cndmask_b32_e64 v76, v80, v76, s[12:13]
	v_cndmask_b32_e64 v74, v74, v78, s[12:13]
	s_nop 1
	v_add_f32_dpp v75, v75, v75 quad_perm:[1,0,3,2] row_mask:0xf bank_mask:0xf
	v_add_f32_dpp v76, v76, v76 quad_perm:[1,0,3,2] row_mask:0xf bank_mask:0xf
	v_add_f32_dpp v77, v77, v77 quad_perm:[1,0,3,2] row_mask:0xf bank_mask:0xf
	v_add_f32_dpp v74, v74, v74 quad_perm:[1,0,3,2] row_mask:0xf bank_mask:0xf
	v_cndmask_b32_e64 v75, v77, v75, s[14:15]
	v_cndmask_b32_e64 v74, v74, v76, s[14:15]
	global_store_dword v[200:201], v75, off
	global_store_dword v[200:201], v74, off offset:32
	v_lshl_add_u64 v[198:199], v[198:199], 0, s[40:41]
	v_add_u32_e32 v165, 0x400, v165
	v_lshl_add_u64 v[200:201], v[200:201], 0, s[42:43]
	s_and_b64 vcc, exec, s[28:29]
	s_cbranch_vccnz .LBB0_681
; DI float bflo(u32 u) { return __uint_as_float(u << 16); }
; DI float bfhi(u32 u) { return __uint_as_float(u & 0xffff0000u); }
; DI void dn2_issue(u32x4 (&W)[16], const int* pl, const unsigned char* wbase, int grp) {
; #pragma unroll
;   for (int j = 0; j < 16; ++j) W[j] = *(const u32x4*)(wbase + (size_t)pl[8 * j + grp] * 1024);
; }
; DI void dn2_math(const u32x4 (&W)[16], u32x4 x0, u32x4 x1, float* __restrict__ parow, int lane) {
;   f2 xf[8];
; #pragma unroll
;   for (int q = 0; q < 4; ++q) { xf[q] = f2{bflo(x0[q]), bfhi(x0[q])}; xf[4 + q] = f2{bflo(x1[q]), bfhi(x1[q])}; }
;   float pv[16];
; #pragma unroll
;   for (int j = 0; j < 16; ++j) {
;     f2 s2 = {0.f, 0.f};
; #pragma unroll
;     for (int d = 0; d < 4; ++d) {
;       f2 lo = __builtin_amdgcn_cvt_pk_f32_fp8((int)W[j][d], false);
;       f2 hi = __builtin_amdgcn_cvt_pk_f32_fp8((int)W[j][d], true);
;       s2 = lo * xf[2 * d] + s2;
;       s2 = hi * xf[2 * d + 1] + s2;
;     }
;     pv[j] = s2.x + s2.y;
.LBB0_694:
	ds_read2_b32 v[134:135], v165 offset1:8
	ds_read2_b32 v[126:127], v165 offset0:16 offset1:24
	ds_read2_b32 v[118:119], v165 offset0:32 offset1:40
	ds_read2_b32 v[110:111], v165 offset0:48 offset1:56
	ds_read2_b32 v[102:103], v165 offset0:64 offset1:72
	ds_read2_b32 v[94:95], v165 offset0:80 offset1:88
	ds_read2_b32 v[86:87], v165 offset0:96 offset1:104
	ds_read2_b32 v[78:79], v165 offset0:112 offset1:120
	s_waitcnt lgkmcnt(7)
	v_lshl_add_u32 v130, v135, 10, v250
	v_lshl_add_u32 v134, v134, 10, v250
	global_load_dwordx4 v[134:137], v134, s[98:99]
	global_load_dwordx4 v[130:133], v130, s[98:99]
	s_waitcnt lgkmcnt(6)
	v_lshl_add_u32 v122, v127, 10, v250
	v_lshl_add_u32 v126, v126, 10, v250
	global_load_dwordx4 v[126:129], v126, s[98:99]
	global_load_dwordx4 v[122:125], v122, s[98:99]
	s_waitcnt lgkmcnt(5)
	v_lshl_add_u32 v114, v119, 10, v250
	v_lshl_add_u32 v118, v118, 10, v250
	global_load_dwordx4 v[118:121], v118, s[98:99]
	global_load_dwordx4 v[114:117], v114, s[98:99]
	s_waitcnt lgkmcnt(4)
	v_lshl_add_u32 v106, v111, 10, v250
	v_lshl_add_u32 v110, v110, 10, v250
	global_load_dwordx4 v[110:113], v110, s[98:99]
	global_load_dwordx4 v[106:109], v106, s[98:99]
	s_waitcnt lgkmcnt(3)
	v_lshl_add_u32 v98, v103, 10, v250
	v_lshl_add_u32 v102, v102, 10, v250
	global_load_dwordx4 v[102:105], v102, s[98:99]
	global_load_dwordx4 v[98:101], v98, s[98:99]
	s_waitcnt lgkmcnt(2)
	v_lshl_add_u32 v90, v95, 10, v250
	v_lshl_add_u32 v94, v94, 10, v250
	global_load_dwordx4 v[94:97], v94, s[98:99]
	global_load_dwordx4 v[90:93], v90, s[98:99]
	s_waitcnt lgkmcnt(1)
	v_lshl_add_u32 v82, v87, 10, v250
	v_lshl_add_u32 v86, v86, 10, v250
	global_load_dwordx4 v[86:89], v86, s[98:99]
	global_load_dwordx4 v[82:85], v82, s[98:99]
	s_waitcnt lgkmcnt(0)
	v_lshl_add_u32 v74, v79, 10, v250
	v_lshl_add_u32 v78, v78, 10, v250
	global_load_dwordx4 v[78:81], v78, s[98:99]
	global_load_dwordx4 v[74:77], v74, s[98:99]
	s_nop 0
	global_load_dwordx4 v[138:141], v[198:199], off offset:-2032
	global_load_dwordx4 v[142:145], v[198:199], off offset:-2048
	s_waitcnt vmcnt(35)
	v_cvt_pk_f32_fp8_e32 v[230:231], v2
	v_cvt_pk_f32_fp8_sdwa v[232:233], v2 src0_sel:WORD_1
	v_cvt_pk_f32_fp8_e32 v[234:235], v3
	s_waitcnt vmcnt(18)
	v_lshlrev_b32_e32 v210, 16, v70
	v_and_b32_e32 v211, 0xffff0000, v70
	v_cvt_pk_f32_fp8_sdwa v[236:237], v3 src0_sel:WORD_1
	v_lshlrev_b32_e32 v212, 16, v71
	v_and_b32_e32 v213, 0xffff0000, v71
	v_pk_fma_f32 v[230:231], v[230:231], v[210:211], 0 op_sel_hi:[1,1,0]
	v_lshlrev_b32_e32 v214, 16, v72
	v_and_b32_e32 v215, 0xffff0000, v72
	v_pk_fma_f32 v[230:231], v[232:233], v[212:213], v[230:231]
	v_cvt_pk_f32_fp8_e32 v[232:233], v4
	v_lshlrev_b32_e32 v216, 16, v73
	v_and_b32_e32 v217, 0xffff0000, v73
	v_pk_fma_f32 v[230:231], v[234:235], v[214:215], v[230:231]
	v_cvt_pk_f32_fp8_sdwa v[234:235], v4 src0_sel:WORD_1
	v_pk_fma_f32 v[230:231], v[236:237], v[216:217], v[230:231]
	v_cvt_pk_f32_fp8_e32 v[236:237], v5
	v_lshlrev_b32_e32 v202, 16, v66
	v_and_b32_e32 v203, 0xffff0000, v66
	v_cvt_pk_f32_fp8_sdwa v[238:239], v5 src0_sel:WORD_1
	v_lshlrev_b32_e32 v204, 16, v67
	v_and_b32_e32 v205, 0xffff0000, v67
	v_pk_fma_f32 v[230:231], v[232:233], v[202:203], v[230:231]
	v_lshlrev_b32_e32 v206, 16, v68
	v_and_b32_e32 v207, 0xffff0000, v68
	v_pk_fma_f32 v[230:231], v[234:235], v[204:205], v[230:231]
	v_lshlrev_b32_e32 v208, 16, v69
	v_and_b32_e32 v209, 0xffff0000, v69
	v_pk_fma_f32 v[230:231], v[236:237], v[206:207], v[230:231]
	v_cvt_pk_f32_fp8_sdwa v[232:233], v6 src0_sel:WORD_1
	v_pk_fma_f32 v[230:231], v[238:239], v[208:209], v[230:231]
	v_cvt_pk_f32_fp8_e32 v[234:235], v7
	v_add_f32_e32 v167, v230, v231
	v_cvt_pk_f32_fp8_e32 v[230:231], v6
	v_cvt_pk_f32_fp8_sdwa v[236:237], v7 src0_sel:WORD_1
	v_cvt_pk_f32_fp8_sdwa v[238:239], v9 src0_sel:WORD_1
	v_pk_fma_f32 v[230:231], v[230:231], v[210:211], 0 op_sel_hi:[1,1,0]
	s_nop 0
	v_pk_fma_f32 v[230:231], v[232:233], v[212:213], v[230:231]
	v_cvt_pk_f32_fp8_e32 v[232:233], v8
	v_pk_fma_f32 v[230:231], v[234:235], v[214:215], v[230:231]
	v_cvt_pk_f32_fp8_sdwa v[234:235], v8 src0_sel:WORD_1
	v_pk_fma_f32 v[230:231], v[236:237], v[216:217], v[230:231]
	v_cvt_pk_f32_fp8_e32 v[236:237], v9
	v_pk_fma_f32 v[230:231], v[232:233], v[202:203], v[230:231]
	v_cvt_pk_f32_fp8_sdwa v[232:233], v10 src0_sel:WORD_1
	v_pk_fma_f32 v[230:231], v[234:235], v[204:205], v[230:231]
	v_cvt_pk_f32_fp8_e32 v[234:235], v11
	v_pk_fma_f32 v[230:231], v[236:237], v[206:207], v[230:231]
	v_cvt_pk_f32_fp8_sdwa v[236:237], v11 src0_sel:WORD_1
	v_pk_fma_f32 v[230:231], v[238:239], v[208:209], v[230:231]
	v_cvt_pk_f32_fp8_sdwa v[238:239], v13 src0_sel:WORD_1
	v_add_f32_e32 v169, v230, v231
	v_cvt_pk_f32_fp8_e32 v[230:231], v10
	v_pk_fma_f32 v[230:231], v[230:231], v[210:211], 0 op_sel_hi:[1,1,0]
	s_nop 0
	v_pk_fma_f32 v[230:231], v[232:233], v[212:213], v[230:231]
	v_cvt_pk_f32_fp8_e32 v[232:233], v12
	v_pk_fma_f32 v[230:231], v[234:235], v[214:215], v[230:231]
	v_cvt_pk_f32_fp8_sdwa v[234:235], v12 src0_sel:WORD_1
	v_pk_fma_f32 v[230:231], v[236:237], v[216:217], v[230:231]
	v_cvt_pk_f32_fp8_e32 v[236:237], v13
	v_pk_fma_f32 v[230:231], v[232:233], v[202:203], v[230:231]
	v_cvt_pk_f32_fp8_sdwa v[232:233], v14 src0_sel:WORD_1
	v_pk_fma_f32 v[230:231], v[234:235], v[204:205], v[230:231]
	v_cvt_pk_f32_fp8_e32 v[234:235], v15
	v_pk_fma_f32 v[230:231], v[236:237], v[206:207], v[230:231]
	v_cvt_pk_f32_fp8_sdwa v[236:237], v15 src0_sel:WORD_1
	v_pk_fma_f32 v[230:231], v[238:239], v[208:209], v[230:231]
	v_cvt_pk_f32_fp8_sdwa v[238:239], v17 src0_sel:WORD_1
	v_add_f32_e32 v171, v230, v231
	v_cvt_pk_f32_fp8_e32 v[230:231], v14
	v_pk_fma_f32 v[230:231], v[230:231], v[210:211], 0 op_sel_hi:[1,1,0]
; DI void dn2_math(const u32x4 (&W)[16], u32x4 x0, u32x4 x1, float* __restrict__ parow, int lane) {
;     ...
;   for (int j = 0; j < 16; ++j) {
;     f2 s2 = {0.f, 0.f};
; #pragma unroll
;     for (int d = 0; d < 4; ++d) {
;       f2 lo = __builtin_amdgcn_cvt_pk_f32_fp8((int)W[j][d], false);
;       f2 hi = __builtin_amdgcn_cvt_pk_f32_fp8((int)W[j][d], true);
;       s2 = lo * xf[2 * d] + s2;
;       s2 = hi * xf[2 * d + 1] + s2;
;     }
;     pv[j] = s2.x + s2.y;
	s_nop 0
	v_pk_fma_f32 v[230:231], v[232:233], v[212:213], v[230:231]
	v_cvt_pk_f32_fp8_e32 v[232:233], v16
	v_pk_fma_f32 v[230:231], v[234:235], v[214:215], v[230:231]
	v_cvt_pk_f32_fp8_sdwa v[234:235], v16 src0_sel:WORD_1
	v_pk_fma_f32 v[230:231], v[236:237], v[216:217], v[230:231]
	v_cvt_pk_f32_fp8_e32 v[236:237], v17
	v_pk_fma_f32 v[230:231], v[232:233], v[202:203], v[230:231]
	v_cvt_pk_f32_fp8_sdwa v[232:233], v18 src0_sel:WORD_1
	v_pk_fma_f32 v[230:231], v[234:235], v[204:205], v[230:231]
	v_cvt_pk_f32_fp8_e32 v[234:235], v19
	v_pk_fma_f32 v[230:231], v[236:237], v[206:207], v[230:231]
	v_cvt_pk_f32_fp8_sdwa v[236:237], v19 src0_sel:WORD_1
	v_pk_fma_f32 v[230:231], v[238:239], v[208:209], v[230:231]
	v_cvt_pk_f32_fp8_sdwa v[238:239], v21 src0_sel:WORD_1
	v_add_f32_e32 v173, v230, v231
	v_cvt_pk_f32_fp8_e32 v[230:231], v18
	v_pk_fma_f32 v[230:231], v[230:231], v[210:211], 0 op_sel_hi:[1,1,0]
	s_nop 0
	v_pk_fma_f32 v[230:231], v[232:233], v[212:213], v[230:231]
	v_cvt_pk_f32_fp8_e32 v[232:233], v20
	v_pk_fma_f32 v[230:231], v[234:235], v[214:215], v[230:231]
	v_cvt_pk_f32_fp8_sdwa v[234:235], v20 src0_sel:WORD_1
	v_pk_fma_f32 v[230:231], v[236:237], v[216:217], v[230:231]
	v_cvt_pk_f32_fp8_e32 v[236:237], v21
	v_pk_fma_f32 v[230:231], v[232:233], v[202:203], v[230:231]
	v_cvt_pk_f32_fp8_sdwa v[232:233], v22 src0_sel:WORD_1
	v_pk_fma_f32 v[230:231], v[234:235], v[204:205], v[230:231]
	v_cvt_pk_f32_fp8_e32 v[234:235], v23
	v_pk_fma_f32 v[230:231], v[236:237], v[206:207], v[230:231]
	v_cvt_pk_f32_fp8_sdwa v[236:237], v23 src0_sel:WORD_1
	v_pk_fma_f32 v[230:231], v[238:239], v[208:209], v[230:231]
	v_cvt_pk_f32_fp8_sdwa v[238:239], v25 src0_sel:WORD_1
	v_add_f32_e32 v175, v230, v231
	v_cvt_pk_f32_fp8_e32 v[230:231], v22
	v_pk_fma_f32 v[230:231], v[230:231], v[210:211], 0 op_sel_hi:[1,1,0]
	s_nop 0
	v_pk_fma_f32 v[230:231], v[232:233], v[212:213], v[230:231]
	v_cvt_pk_f32_fp8_e32 v[232:233], v24
	v_pk_fma_f32 v[230:231], v[234:235], v[214:215], v[230:231]
	v_cvt_pk_f32_fp8_sdwa v[234:235], v24 src0_sel:WORD_1
	v_pk_fma_f32 v[230:231], v[236:237], v[216:217], v[230:231]
	v_cvt_pk_f32_fp8_e32 v[236:237], v25
	v_pk_fma_f32 v[230:231], v[232:233], v[202:203], v[230:231]
	v_cvt_pk_f32_fp8_sdwa v[232:233], v26 src0_sel:WORD_1
	v_pk_fma_f32 v[230:231], v[234:235], v[204:205], v[230:231]
	v_cvt_pk_f32_fp8_e32 v[234:235], v27
	v_pk_fma_f32 v[230:231], v[236:237], v[206:207], v[230:231]
	v_cvt_pk_f32_fp8_sdwa v[236:237], v27 src0_sel:WORD_1
	v_pk_fma_f32 v[230:231], v[238:239], v[208:209], v[230:231]
	v_cvt_pk_f32_fp8_sdwa v[238:239], v29 src0_sel:WORD_1
	v_add_f32_e32 v177, v230, v231
	v_cvt_pk_f32_fp8_e32 v[230:231], v26
	v_pk_fma_f32 v[230:231], v[230:231], v[210:211], 0 op_sel_hi:[1,1,0]
	s_nop 0
	v_pk_fma_f32 v[230:231], v[232:233], v[212:213], v[230:231]
	v_cvt_pk_f32_fp8_e32 v[232:233], v28
	v_pk_fma_f32 v[230:231], v[234:235], v[214:215], v[230:231]
	v_cvt_pk_f32_fp8_sdwa v[234:235], v28 src0_sel:WORD_1
	v_pk_fma_f32 v[230:231], v[236:237], v[216:217], v[230:231]
	v_cvt_pk_f32_fp8_e32 v[236:237], v29
	v_pk_fma_f32 v[230:231], v[232:233], v[202:203], v[230:231]
	v_cvt_pk_f32_fp8_sdwa v[232:233], v30 src0_sel:WORD_1
	v_pk_fma_f32 v[230:231], v[234:235], v[204:205], v[230:231]
	v_cvt_pk_f32_fp8_e32 v[234:235], v31
	v_pk_fma_f32 v[230:231], v[236:237], v[206:207], v[230:231]
	v_cvt_pk_f32_fp8_sdwa v[236:237], v31 src0_sel:WORD_1
	v_pk_fma_f32 v[230:231], v[238:239], v[208:209], v[230:231]
	v_cvt_pk_f32_fp8_sdwa v[238:239], v33 src0_sel:WORD_1
	v_add_f32_e32 v179, v230, v231
	v_cvt_pk_f32_fp8_e32 v[230:231], v30
	v_pk_fma_f32 v[230:231], v[230:231], v[210:211], 0 op_sel_hi:[1,1,0]
	s_nop 0
	v_pk_fma_f32 v[230:231], v[232:233], v[212:213], v[230:231]
	v_cvt_pk_f32_fp8_e32 v[232:233], v32
	v_pk_fma_f32 v[230:231], v[234:235], v[214:215], v[230:231]
	v_cvt_pk_f32_fp8_sdwa v[234:235], v32 src0_sel:WORD_1
	v_pk_fma_f32 v[230:231], v[236:237], v[216:217], v[230:231]
	v_cvt_pk_f32_fp8_e32 v[236:237], v33
	v_pk_fma_f32 v[230:231], v[232:233], v[202:203], v[230:231]
	v_cvt_pk_f32_fp8_sdwa v[232:233], v34 src0_sel:WORD_1
	v_pk_fma_f32 v[230:231], v[234:235], v[204:205], v[230:231]
	v_cvt_pk_f32_fp8_e32 v[234:235], v35
	v_pk_fma_f32 v[230:231], v[236:237], v[206:207], v[230:231]
	v_cvt_pk_f32_fp8_sdwa v[236:237], v35 src0_sel:WORD_1
	v_pk_fma_f32 v[230:231], v[238:239], v[208:209], v[230:231]
	v_cvt_pk_f32_fp8_sdwa v[238:239], v37 src0_sel:WORD_1
	v_add_f32_e32 v181, v230, v231
	v_cvt_pk_f32_fp8_e32 v[230:231], v34
	v_pk_fma_f32 v[230:231], v[230:231], v[210:211], 0 op_sel_hi:[1,1,0]
	s_nop 0
	v_pk_fma_f32 v[230:231], v[232:233], v[212:213], v[230:231]
	v_cvt_pk_f32_fp8_e32 v[232:233], v36
	v_pk_fma_f32 v[230:231], v[234:235], v[214:215], v[230:231]
	v_cvt_pk_f32_fp8_sdwa v[234:235], v36 src0_sel:WORD_1
	v_pk_fma_f32 v[230:231], v[236:237], v[216:217], v[230:231]
	v_cvt_pk_f32_fp8_e32 v[236:237], v37
	v_pk_fma_f32 v[230:231], v[232:233], v[202:203], v[230:231]
	v_cvt_pk_f32_fp8_sdwa v[232:233], v38 src0_sel:WORD_1
	v_pk_fma_f32 v[230:231], v[234:235], v[204:205], v[230:231]
	v_cvt_pk_f32_fp8_e32 v[234:235], v39
	v_pk_fma_f32 v[230:231], v[236:237], v[206:207], v[230:231]
	v_cvt_pk_f32_fp8_sdwa v[236:237], v39 src0_sel:WORD_1
	v_pk_fma_f32 v[230:231], v[238:239], v[208:209], v[230:231]
	v_cvt_pk_f32_fp8_sdwa v[238:239], v41 src0_sel:WORD_1
	v_add_f32_e32 v183, v230, v231
	v_cvt_pk_f32_fp8_e32 v[230:231], v38
	v_pk_fma_f32 v[230:231], v[230:231], v[210:211], 0 op_sel_hi:[1,1,0]
	s_nop 0
	v_pk_fma_f32 v[230:231], v[232:233], v[212:213], v[230:231]
	v_cvt_pk_f32_fp8_e32 v[232:233], v40
	v_pk_fma_f32 v[230:231], v[234:235], v[214:215], v[230:231]
; DI void dn2_math(const u32x4 (&W)[16], u32x4 x0, u32x4 x1, float* __restrict__ parow, int lane) {
;     ...
;   for (int j = 0; j < 16; ++j) {
;     f2 s2 = {0.f, 0.f};
; #pragma unroll
;     for (int d = 0; d < 4; ++d) {
;       f2 lo = __builtin_amdgcn_cvt_pk_f32_fp8((int)W[j][d], false);
;       f2 hi = __builtin_amdgcn_cvt_pk_f32_fp8((int)W[j][d], true);
;       s2 = lo * xf[2 * d] + s2;
;       s2 = hi * xf[2 * d + 1] + s2;
;     }
;     pv[j] = s2.x + s2.y;
	v_cvt_pk_f32_fp8_sdwa v[234:235], v40 src0_sel:WORD_1
	v_pk_fma_f32 v[230:231], v[236:237], v[216:217], v[230:231]
	v_cvt_pk_f32_fp8_e32 v[236:237], v41
	v_pk_fma_f32 v[230:231], v[232:233], v[202:203], v[230:231]
	v_cvt_pk_f32_fp8_sdwa v[232:233], v42 src0_sel:WORD_1
	v_pk_fma_f32 v[230:231], v[234:235], v[204:205], v[230:231]
	v_cvt_pk_f32_fp8_e32 v[234:235], v43
	v_pk_fma_f32 v[230:231], v[236:237], v[206:207], v[230:231]
	v_cvt_pk_f32_fp8_sdwa v[236:237], v43 src0_sel:WORD_1
	v_pk_fma_f32 v[230:231], v[238:239], v[208:209], v[230:231]
	v_cvt_pk_f32_fp8_sdwa v[238:239], v45 src0_sel:WORD_1
	v_add_f32_e32 v185, v230, v231
	v_cvt_pk_f32_fp8_e32 v[230:231], v42
	v_pk_fma_f32 v[230:231], v[230:231], v[210:211], 0 op_sel_hi:[1,1,0]
	s_nop 0
	v_pk_fma_f32 v[230:231], v[232:233], v[212:213], v[230:231]
	v_cvt_pk_f32_fp8_e32 v[232:233], v44
	v_pk_fma_f32 v[230:231], v[234:235], v[214:215], v[230:231]
	v_cvt_pk_f32_fp8_sdwa v[234:235], v44 src0_sel:WORD_1
	v_pk_fma_f32 v[230:231], v[236:237], v[216:217], v[230:231]
	v_cvt_pk_f32_fp8_e32 v[236:237], v45
	v_pk_fma_f32 v[230:231], v[232:233], v[202:203], v[230:231]
	v_cvt_pk_f32_fp8_sdwa v[232:233], v46 src0_sel:WORD_1
	v_pk_fma_f32 v[230:231], v[234:235], v[204:205], v[230:231]
	v_cvt_pk_f32_fp8_e32 v[234:235], v47
	v_pk_fma_f32 v[230:231], v[236:237], v[206:207], v[230:231]
	v_cvt_pk_f32_fp8_sdwa v[236:237], v47 src0_sel:WORD_1
	v_pk_fma_f32 v[230:231], v[238:239], v[208:209], v[230:231]
	v_cvt_pk_f32_fp8_sdwa v[238:239], v49 src0_sel:WORD_1
	v_add_f32_e32 v187, v230, v231
	v_cvt_pk_f32_fp8_e32 v[230:231], v46
	v_pk_fma_f32 v[230:231], v[230:231], v[210:211], 0 op_sel_hi:[1,1,0]
	s_nop 0
	v_pk_fma_f32 v[230:231], v[232:233], v[212:213], v[230:231]
	v_cvt_pk_f32_fp8_e32 v[232:233], v48
	v_pk_fma_f32 v[230:231], v[234:235], v[214:215], v[230:231]
	v_cvt_pk_f32_fp8_sdwa v[234:235], v48 src0_sel:WORD_1
	v_pk_fma_f32 v[230:231], v[236:237], v[216:217], v[230:231]
	v_cvt_pk_f32_fp8_e32 v[236:237], v49
	v_pk_fma_f32 v[230:231], v[232:233], v[202:203], v[230:231]
	v_cvt_pk_f32_fp8_sdwa v[232:233], v50 src0_sel:WORD_1
	v_pk_fma_f32 v[230:231], v[234:235], v[204:205], v[230:231]
	v_cvt_pk_f32_fp8_e32 v[234:235], v51
	v_pk_fma_f32 v[230:231], v[236:237], v[206:207], v[230:231]
	v_cvt_pk_f32_fp8_sdwa v[236:237], v51 src0_sel:WORD_1
	v_pk_fma_f32 v[230:231], v[238:239], v[208:209], v[230:231]
	v_cvt_pk_f32_fp8_sdwa v[238:239], v53 src0_sel:WORD_1
	v_add_f32_e32 v189, v230, v231
	v_cvt_pk_f32_fp8_e32 v[230:231], v50
	v_pk_fma_f32 v[230:231], v[230:231], v[210:211], 0 op_sel_hi:[1,1,0]
	s_nop 0
	v_pk_fma_f32 v[230:231], v[232:233], v[212:213], v[230:231]
	v_cvt_pk_f32_fp8_e32 v[232:233], v52
	v_pk_fma_f32 v[230:231], v[234:235], v[214:215], v[230:231]
	v_cvt_pk_f32_fp8_sdwa v[234:235], v52 src0_sel:WORD_1
	v_pk_fma_f32 v[230:231], v[236:237], v[216:217], v[230:231]
	v_cvt_pk_f32_fp8_e32 v[236:237], v53
	v_pk_fma_f32 v[230:231], v[232:233], v[202:203], v[230:231]
	v_cvt_pk_f32_fp8_sdwa v[232:233], v54 src0_sel:WORD_1
	v_pk_fma_f32 v[230:231], v[234:235], v[204:205], v[230:231]
	v_cvt_pk_f32_fp8_e32 v[234:235], v55
	v_pk_fma_f32 v[230:231], v[236:237], v[206:207], v[230:231]
	v_cvt_pk_f32_fp8_sdwa v[236:237], v55 src0_sel:WORD_1
	v_pk_fma_f32 v[230:231], v[238:239], v[208:209], v[230:231]
	v_cvt_pk_f32_fp8_sdwa v[238:239], v57 src0_sel:WORD_1
	v_add_f32_e32 v240, v230, v231
	v_cvt_pk_f32_fp8_e32 v[230:231], v54
	v_pk_fma_f32 v[230:231], v[230:231], v[210:211], 0 op_sel_hi:[1,1,0]
	s_nop 0
	v_pk_fma_f32 v[230:231], v[232:233], v[212:213], v[230:231]
	v_cvt_pk_f32_fp8_e32 v[232:233], v56
	v_pk_fma_f32 v[230:231], v[234:235], v[214:215], v[230:231]
	v_cvt_pk_f32_fp8_sdwa v[234:235], v56 src0_sel:WORD_1
	v_pk_fma_f32 v[230:231], v[236:237], v[216:217], v[230:231]
	v_cvt_pk_f32_fp8_e32 v[236:237], v57
	v_pk_fma_f32 v[230:231], v[232:233], v[202:203], v[230:231]
	v_cvt_pk_f32_fp8_sdwa v[232:233], v58 src0_sel:WORD_1
	v_pk_fma_f32 v[230:231], v[234:235], v[204:205], v[230:231]
	v_cvt_pk_f32_fp8_e32 v[234:235], v59
	v_pk_fma_f32 v[230:231], v[236:237], v[206:207], v[230:231]
	v_cvt_pk_f32_fp8_sdwa v[236:237], v59 src0_sel:WORD_1
	v_pk_fma_f32 v[230:231], v[238:239], v[208:209], v[230:231]
	v_cvt_pk_f32_fp8_sdwa v[238:239], v61 src0_sel:WORD_1
	v_add_f32_e32 v241, v230, v231
	v_cvt_pk_f32_fp8_e32 v[230:231], v58
	v_pk_fma_f32 v[230:231], v[230:231], v[210:211], 0 op_sel_hi:[1,1,0]
	s_nop 0
	v_pk_fma_f32 v[230:231], v[232:233], v[212:213], v[230:231]
	v_cvt_pk_f32_fp8_e32 v[232:233], v60
	v_pk_fma_f32 v[230:231], v[234:235], v[214:215], v[230:231]
	v_cvt_pk_f32_fp8_sdwa v[234:235], v60 src0_sel:WORD_1
	v_pk_fma_f32 v[230:231], v[236:237], v[216:217], v[230:231]
	v_cvt_pk_f32_fp8_e32 v[236:237], v61
	v_pk_fma_f32 v[230:231], v[232:233], v[202:203], v[230:231]
	v_cvt_pk_f32_fp8_sdwa v[232:233], v62 src0_sel:WORD_1
	v_pk_fma_f32 v[230:231], v[234:235], v[204:205], v[230:231]
	v_cvt_pk_f32_fp8_e32 v[234:235], v63
	v_pk_fma_f32 v[230:231], v[236:237], v[206:207], v[230:231]
	v_cvt_pk_f32_fp8_sdwa v[236:237], v63 src0_sel:WORD_1
	v_pk_fma_f32 v[230:231], v[238:239], v[208:209], v[230:231]
	s_nop 0
	v_add_f32_e32 v238, v230, v231
	v_cvt_pk_f32_fp8_e32 v[230:231], v62
	v_pk_fma_f32 v[210:211], v[230:231], v[210:211], 0 op_sel_hi:[1,1,0]
; DI void dn2_math(const u32x4 (&W)[16], u32x4 x0, u32x4 x1, float* __restrict__ parow, int lane) {
;     ...
;   const bool b2 = lane & 4, b1 = lane & 2, b0 = lane & 1;
;   float q8[8];
; #pragma unroll
;   for (int i = 0; i < 8; ++i) { float snd = b2 ? pv[i] : pv[i + 8]; float kp = b2 ? pv[i + 8] : pv[i]; q8[i] = kp + __shfl_xor(snd, 4); }
;   float q4[4];
; #pragma unroll
;   for (int i = 0; i < 4; ++i) { float snd = b1 ? q8[i] : q8[i + 4]; float kp = b1 ? q8[i + 4] : q8[i]; q4[i] = kp + __shfl_xor(snd, 2); }
;   float r2[2];
; #pragma unroll
;   for (int i = 0; i < 2; ++i) { float snd = b0 ? q4[i] : q4[i + 2]; float kp = b0 ? q4[i + 2] : q4[i]; r2[i] = kp + __shfl_xor(snd, 1); }
;   const int j0 = (b0 ? 2 : 0) + (b1 ? 4 : 0) + (b2 ? 8 : 0);
;   const int grp = lane >> 3;
;   parow[8 * j0 + grp] = r2[0];
;   parow[8 * (j0 + 1) + grp] = r2[1];
; DI void peer_down2_phase(const Params& p, unsigned char* smem, int layer, const bf16* __restrict__ x1b, u32* ctr) {
;     ...
;         if (tl + 2 < 16) {
;           dn2_issue(WA, pl + (tl + 2) * 128, wbase, grp);
;           xa0 = *(const u32x4*)(xb0 + (size_t)(tl + 2) * 1024); xa1 = *(const u32x4*)(xb0 + (size_t)(tl + 2) * 1024 + 8);
;         }
	s_nop 0
	v_pk_fma_f32 v[210:211], v[232:233], v[212:213], v[210:211]
	v_cvt_pk_f32_fp8_e32 v[212:213], v64
	v_pk_fma_f32 v[210:211], v[234:235], v[214:215], v[210:211]
	v_cvt_pk_f32_fp8_sdwa v[214:215], v64 src0_sel:WORD_1
	v_pk_fma_f32 v[210:211], v[236:237], v[216:217], v[210:211]
	v_cvt_pk_f32_fp8_e32 v[216:217], v65
	v_cvt_pk_f32_fp8_sdwa v[230:231], v65 src0_sel:WORD_1
	v_pk_fma_f32 v[202:203], v[212:213], v[202:203], v[210:211]
	s_nop 0
	v_pk_fma_f32 v[202:203], v[214:215], v[204:205], v[202:203]
	v_pk_fma_f32 v[202:203], v[216:217], v[206:207], v[202:203]
	v_pk_fma_f32 v[202:203], v[230:231], v[208:209], v[202:203]
	v_add_f32_e32 v202, v202, v203
	s_nop 1
	v_add_f32_dpp v167, v167, v167 row_shl:4 row_mask:0xf bank_mask:0x5
	v_add_f32_dpp v173, v173, v173 row_shl:4 row_mask:0xf bank_mask:0x5
	v_add_f32_dpp v175, v175, v175 row_shl:4 row_mask:0xf bank_mask:0x5
	v_add_f32_dpp v169, v169, v169 row_shl:4 row_mask:0xf bank_mask:0x5
	v_add_f32_dpp v171, v171, v171 row_shl:4 row_mask:0xf bank_mask:0x5
	v_add_f32_dpp v177, v177, v177 row_shl:4 row_mask:0xf bank_mask:0x5
	v_add_f32_dpp v179, v179, v179 row_shl:4 row_mask:0xf bank_mask:0x5
	v_add_f32_dpp v181, v181, v181 row_shl:4 row_mask:0xf bank_mask:0x5
	v_add_f32_dpp v167, v183, v183 row_shr:4 row_mask:0xf bank_mask:0xa
	v_add_f32_dpp v173, v189, v189 row_shr:4 row_mask:0xf bank_mask:0xa
	v_add_f32_dpp v175, v240, v240 row_shr:4 row_mask:0xf bank_mask:0xa
	v_add_f32_dpp v169, v185, v185 row_shr:4 row_mask:0xf bank_mask:0xa
	v_add_f32_dpp v171, v187, v187 row_shr:4 row_mask:0xf bank_mask:0xa
	v_add_f32_dpp v177, v241, v241 row_shr:4 row_mask:0xf bank_mask:0xa
	v_add_f32_dpp v179, v238, v238 row_shr:4 row_mask:0xf bank_mask:0xa
	v_add_f32_dpp v181, v202, v202 row_shr:4 row_mask:0xf bank_mask:0xa
	s_nop 1
	v_add_f32_dpp v167, v167, v167 quad_perm:[2,3,0,1] row_mask:0xf bank_mask:0xf
	v_add_f32_dpp v171, v171, v171 quad_perm:[2,3,0,1] row_mask:0xf bank_mask:0xf
	v_add_f32_dpp v169, v169, v169 quad_perm:[2,3,0,1] row_mask:0xf bank_mask:0xf
	v_add_f32_dpp v173, v173, v173 quad_perm:[2,3,0,1] row_mask:0xf bank_mask:0xf
	v_add_f32_dpp v175, v175, v175 quad_perm:[2,3,0,1] row_mask:0xf bank_mask:0xf
	v_add_f32_dpp v179, v179, v179 quad_perm:[2,3,0,1] row_mask:0xf bank_mask:0xf
	v_add_f32_dpp v177, v177, v177 quad_perm:[2,3,0,1] row_mask:0xf bank_mask:0xf
	v_add_f32_dpp v181, v181, v181 quad_perm:[2,3,0,1] row_mask:0xf bank_mask:0xf
	v_cndmask_b32_e64 v167, v175, v167, s[12:13]
	v_cndmask_b32_e64 v171, v179, v171, s[12:13]
	v_cndmask_b32_e64 v169, v177, v169, s[12:13]
	v_cndmask_b32_e64 v173, v181, v173, s[12:13]
	s_nop 1
	v_add_f32_dpp v167, v167, v167 quad_perm:[1,0,3,2] row_mask:0xf bank_mask:0xf
	v_add_f32_dpp v169, v169, v169 quad_perm:[1,0,3,2] row_mask:0xf bank_mask:0xf
	v_add_f32_dpp v171, v171, v171 quad_perm:[1,0,3,2] row_mask:0xf bank_mask:0xf
	v_add_f32_dpp v173, v173, v173 quad_perm:[1,0,3,2] row_mask:0xf bank_mask:0xf
	v_cndmask_b32_e64 v167, v171, v167, s[14:15]
	v_cndmask_b32_e64 v169, v173, v169, s[14:15]
	global_store_dword v[200:201], v167, off offset:-512
	global_store_dword v[200:201], v169, off offset:-480
	s_cmp_gt_u32 s46, 13
	s_cselect_b64 s[28:29], -1, 0
	s_and_b64 vcc, exec, s[28:29]
	s_cbranch_vccnz .LBB0_693
	ds_read2_b32 v[2:3], v165 offset0:128 offset1:136
	ds_read2_b32 v[10:11], v165 offset0:144 offset1:152
	ds_read2_b32 v[18:19], v165 offset0:160 offset1:168
	ds_read2_b32 v[26:27], v165 offset0:176 offset1:184
	ds_read2_b32 v[34:35], v165 offset0:192 offset1:200
	ds_read2_b32 v[42:43], v165 offset0:208 offset1:216
	ds_read2_b32 v[50:51], v165 offset0:224 offset1:232
	ds_read2_b32 v[58:59], v165 offset0:240 offset1:248
	s_waitcnt lgkmcnt(7)
	v_lshl_add_u32 v6, v3, 10, v250
	v_lshl_add_u32 v2, v2, 10, v250
	global_load_dwordx4 v[2:5], v2, s[98:99]
	global_load_dwordx4 v[6:9], v6, s[98:99]
	s_waitcnt lgkmcnt(6)
	v_lshl_add_u32 v14, v11, 10, v250
	v_lshl_add_u32 v10, v10, 10, v250
	global_load_dwordx4 v[10:13], v10, s[98:99]
	global_load_dwordx4 v[14:17], v14, s[98:99]
	s_waitcnt lgkmcnt(5)
	v_lshl_add_u32 v22, v19, 10, v250
	v_lshl_add_u32 v18, v18, 10, v250
	global_load_dwordx4 v[18:21], v18, s[98:99]
	global_load_dwordx4 v[22:25], v22, s[98:99]
	s_waitcnt lgkmcnt(4)
	v_lshl_add_u32 v30, v27, 10, v250
	v_lshl_add_u32 v26, v26, 10, v250
	global_load_dwordx4 v[26:29], v26, s[98:99]
	global_load_dwordx4 v[30:33], v30, s[98:99]
	s_waitcnt lgkmcnt(3)
	v_lshl_add_u32 v38, v35, 10, v250
	v_lshl_add_u32 v34, v34, 10, v250
	global_load_dwordx4 v[34:37], v34, s[98:99]
	global_load_dwordx4 v[38:41], v38, s[98:99]
	s_waitcnt lgkmcnt(2)
	v_lshl_add_u32 v46, v43, 10, v250
	v_lshl_add_u32 v42, v42, 10, v250
	global_load_dwordx4 v[42:45], v42, s[98:99]
	global_load_dwordx4 v[46:49], v46, s[98:99]
	s_waitcnt lgkmcnt(1)
	v_lshl_add_u32 v54, v51, 10, v250
	v_lshl_add_u32 v50, v50, 10, v250
	global_load_dwordx4 v[50:53], v50, s[98:99]
	global_load_dwordx4 v[54:57], v54, s[98:99]
	s_waitcnt lgkmcnt(0)
	v_lshl_add_u32 v62, v59, 10, v250
	v_lshl_add_u32 v58, v58, 10, v250
	global_load_dwordx4 v[58:61], v58, s[98:99]
	global_load_dwordx4 v[62:65], v62, s[98:99]
	s_nop 0
	global_load_dwordx4 v[66:69], v[198:199], off offset:16
	global_load_dwordx4 v[70:73], v[198:199], off
	s_branch .LBB0_693

; DI float bflo(u32 u) { return __uint_as_float(u << 16); }
; DI float bfhi(u32 u) { return __uint_as_float(u & 0xffff0000u); }
; DI void dn2_math(const u32x4 (&W)[16], u32x4 x0, u32x4 x1, float* __restrict__ parow, int lane) {
;   f2 xf[8];
; #pragma unroll
;   for (int q = 0; q < 4; ++q) { xf[q] = f2{bflo(x0[q]), bfhi(x0[q])}; xf[4 + q] = f2{bflo(x1[q]), bfhi(x1[q])}; }
;   float pv[16];
; #pragma unroll
;   for (int j = 0; j < 16; ++j) {
;     f2 s2 = {0.f, 0.f};
; #pragma unroll
;     for (int d = 0; d < 4; ++d) {
;       f2 lo = __builtin_amdgcn_cvt_pk_f32_fp8((int)W[j][d], false);
;       f2 hi = __builtin_amdgcn_cvt_pk_f32_fp8((int)W[j][d], true);
;       s2 = lo * xf[2 * d] + s2;
;       s2 = hi * xf[2 * d + 1] + s2;
;     }
;     pv[j] = s2.x + s2.y;
; DI void peer_down2_phase(const Params& p, unsigned char* smem, int layer, const bf16* __restrict__ x1b, u32* ctr) {
;     ...
;       for (int tl = 0; tl < 16; tl += 2) {
;         dn2_issue(WB, pl + (tl + 1) * 128, wbase, grp);
.LBB0_1516:
	s_add_i32 s40, s40, 2
	s_waitcnt vmcnt(19)
	v_cvt_pk_f32_fp8_e32 v[210:211], v134
	v_cvt_pk_f32_fp8_sdwa v[212:213], v134 src0_sel:WORD_1
	v_cvt_pk_f32_fp8_e32 v[214:215], v135
	s_waitcnt vmcnt(2)
	v_lshlrev_b32_e32 v204, 16, v142
	v_and_b32_e32 v205, 0xffff0000, v142
	v_cvt_pk_f32_fp8_sdwa v[134:135], v135 src0_sel:WORD_1
	v_lshlrev_b32_e32 v206, 16, v143
	v_and_b32_e32 v207, 0xffff0000, v143
	v_pk_fma_f32 v[210:211], v[210:211], v[204:205], 0 op_sel_hi:[1,1,0]
	v_lshlrev_b32_e32 v208, 16, v144
	v_and_b32_e32 v209, 0xffff0000, v144
	v_pk_fma_f32 v[210:211], v[212:213], v[206:207], v[210:211]
	v_lshlrev_b32_e32 v144, 16, v145
	v_and_b32_e32 v145, 0xffff0000, v145
	v_pk_fma_f32 v[210:211], v[214:215], v[208:209], v[210:211]
	v_cvt_pk_f32_fp8_sdwa v[212:213], v136 src0_sel:WORD_1
	v_pk_fma_f32 v[134:135], v[134:135], v[144:145], v[210:211]
	v_cvt_pk_f32_fp8_e32 v[210:211], v136
	v_cvt_pk_f32_fp8_e32 v[214:215], v137
	v_lshlrev_b32_e32 v202, 16, v138
	v_and_b32_e32 v203, 0xffff0000, v138
	v_cvt_pk_f32_fp8_sdwa v[136:137], v137 src0_sel:WORD_1
	v_lshlrev_b32_e32 v138, 16, v139
	v_and_b32_e32 v139, 0xffff0000, v139
	v_pk_fma_f32 v[134:135], v[210:211], v[202:203], v[134:135]
	v_lshlrev_b32_e32 v142, 16, v140
	v_and_b32_e32 v143, 0xffff0000, v140
	v_pk_fma_f32 v[134:135], v[212:213], v[138:139], v[134:135]
	v_lshlrev_b32_e32 v140, 16, v141
	v_and_b32_e32 v141, 0xffff0000, v141
	v_pk_fma_f32 v[134:135], v[214:215], v[142:143], v[134:135]
	v_cvt_pk_f32_fp8_e32 v[210:211], v131
	v_pk_fma_f32 v[134:135], v[136:137], v[140:141], v[134:135]
	v_cvt_pk_f32_fp8_sdwa v[136:137], v130 src0_sel:WORD_1
	v_add_f32_e32 v167, v134, v135
	v_cvt_pk_f32_fp8_e32 v[134:135], v130
	v_cvt_pk_f32_fp8_sdwa v[130:131], v131 src0_sel:WORD_1
	v_pk_fma_f32 v[134:135], v[134:135], v[204:205], 0 op_sel_hi:[1,1,0]
	s_nop 0
	v_pk_fma_f32 v[134:135], v[136:137], v[206:207], v[134:135]
	v_cvt_pk_f32_fp8_sdwa v[136:137], v132 src0_sel:WORD_1
	v_pk_fma_f32 v[134:135], v[210:211], v[208:209], v[134:135]
	v_cvt_pk_f32_fp8_e32 v[210:211], v133
	v_pk_fma_f32 v[130:131], v[130:131], v[144:145], v[134:135]
	v_cvt_pk_f32_fp8_e32 v[134:135], v132
	v_cvt_pk_f32_fp8_sdwa v[132:133], v133 src0_sel:WORD_1
	v_pk_fma_f32 v[130:131], v[134:135], v[202:203], v[130:131]
	s_nop 0
	v_pk_fma_f32 v[130:131], v[136:137], v[138:139], v[130:131]
	v_cvt_pk_f32_fp8_e32 v[134:135], v127
	v_pk_fma_f32 v[130:131], v[210:211], v[142:143], v[130:131]
	s_nop 0
	v_pk_fma_f32 v[130:131], v[132:133], v[140:141], v[130:131]
	v_cvt_pk_f32_fp8_sdwa v[132:133], v126 src0_sel:WORD_1
	v_add_f32_e32 v136, v130, v131
	v_cvt_pk_f32_fp8_e32 v[130:131], v126
	v_cvt_pk_f32_fp8_sdwa v[126:127], v127 src0_sel:WORD_1
	v_pk_fma_f32 v[130:131], v[130:131], v[204:205], 0 op_sel_hi:[1,1,0]
	s_nop 0
	v_pk_fma_f32 v[130:131], v[132:133], v[206:207], v[130:131]
	v_cvt_pk_f32_fp8_sdwa v[132:133], v128 src0_sel:WORD_1
	v_pk_fma_f32 v[130:131], v[134:135], v[208:209], v[130:131]
	v_cvt_pk_f32_fp8_e32 v[134:135], v129
	v_pk_fma_f32 v[126:127], v[126:127], v[144:145], v[130:131]
	v_cvt_pk_f32_fp8_e32 v[130:131], v128
	v_cvt_pk_f32_fp8_sdwa v[128:129], v129 src0_sel:WORD_1
	v_pk_fma_f32 v[126:127], v[130:131], v[202:203], v[126:127]
	s_nop 0
	v_pk_fma_f32 v[126:127], v[132:133], v[138:139], v[126:127]
	v_cvt_pk_f32_fp8_e32 v[130:131], v123
	v_pk_fma_f32 v[126:127], v[134:135], v[142:143], v[126:127]
	s_nop 0
	v_pk_fma_f32 v[126:127], v[128:129], v[140:141], v[126:127]
	v_cvt_pk_f32_fp8_sdwa v[128:129], v122 src0_sel:WORD_1
	v_add_f32_e32 v132, v126, v127
	v_cvt_pk_f32_fp8_e32 v[126:127], v122
	v_cvt_pk_f32_fp8_sdwa v[122:123], v123 src0_sel:WORD_1
	v_pk_fma_f32 v[126:127], v[126:127], v[204:205], 0 op_sel_hi:[1,1,0]
	s_nop 0
	v_pk_fma_f32 v[126:127], v[128:129], v[206:207], v[126:127]
	v_cvt_pk_f32_fp8_sdwa v[128:129], v124 src0_sel:WORD_1
	v_pk_fma_f32 v[126:127], v[130:131], v[208:209], v[126:127]
	v_cvt_pk_f32_fp8_e32 v[130:131], v125
	v_pk_fma_f32 v[122:123], v[122:123], v[144:145], v[126:127]
	v_cvt_pk_f32_fp8_e32 v[126:127], v124
	v_cvt_pk_f32_fp8_sdwa v[124:125], v125 src0_sel:WORD_1
	v_pk_fma_f32 v[122:123], v[126:127], v[202:203], v[122:123]
	s_nop 0
	v_pk_fma_f32 v[122:123], v[128:129], v[138:139], v[122:123]
	v_cvt_pk_f32_fp8_e32 v[126:127], v119
	v_pk_fma_f32 v[122:123], v[130:131], v[142:143], v[122:123]
	s_nop 0
	v_pk_fma_f32 v[122:123], v[124:125], v[140:141], v[122:123]
	v_cvt_pk_f32_fp8_sdwa v[124:125], v118 src0_sel:WORD_1
	v_add_f32_e32 v128, v122, v123
	v_cvt_pk_f32_fp8_e32 v[122:123], v118
	v_cvt_pk_f32_fp8_sdwa v[118:119], v119 src0_sel:WORD_1
	v_pk_fma_f32 v[122:123], v[122:123], v[204:205], 0 op_sel_hi:[1,1,0]
	s_nop 0
	v_pk_fma_f32 v[122:123], v[124:125], v[206:207], v[122:123]
	v_cvt_pk_f32_fp8_sdwa v[124:125], v120 src0_sel:WORD_1
	v_pk_fma_f32 v[122:123], v[126:127], v[208:209], v[122:123]
	v_cvt_pk_f32_fp8_e32 v[126:127], v121
	v_pk_fma_f32 v[118:119], v[118:119], v[144:145], v[122:123]
	v_cvt_pk_f32_fp8_e32 v[122:123], v120
	v_cvt_pk_f32_fp8_sdwa v[120:121], v121 src0_sel:WORD_1
	v_pk_fma_f32 v[118:119], v[122:123], v[202:203], v[118:119]
	s_nop 0
	v_pk_fma_f32 v[118:119], v[124:125], v[138:139], v[118:119]
	v_cvt_pk_f32_fp8_e32 v[122:123], v115
	v_pk_fma_f32 v[118:119], v[126:127], v[142:143], v[118:119]
	s_nop 0
	v_pk_fma_f32 v[118:119], v[120:121], v[140:141], v[118:119]
	v_cvt_pk_f32_fp8_sdwa v[120:121], v114 src0_sel:WORD_1
	v_add_f32_e32 v124, v118, v119
	v_cvt_pk_f32_fp8_e32 v[118:119], v114
	v_cvt_pk_f32_fp8_sdwa v[114:115], v115 src0_sel:WORD_1
	v_pk_fma_f32 v[118:119], v[118:119], v[204:205], 0 op_sel_hi:[1,1,0]
	s_nop 0
	v_pk_fma_f32 v[118:119], v[120:121], v[206:207], v[118:119]
; DI void dn2_math(const u32x4 (&W)[16], u32x4 x0, u32x4 x1, float* __restrict__ parow, int lane) {
;     ...
;   for (int j = 0; j < 16; ++j) {
;     f2 s2 = {0.f, 0.f};
; #pragma unroll
;     for (int d = 0; d < 4; ++d) {
;       f2 lo = __builtin_amdgcn_cvt_pk_f32_fp8((int)W[j][d], false);
;       f2 hi = __builtin_amdgcn_cvt_pk_f32_fp8((int)W[j][d], true);
;       s2 = lo * xf[2 * d] + s2;
;       s2 = hi * xf[2 * d + 1] + s2;
;     }
;     pv[j] = s2.x + s2.y;
	v_cvt_pk_f32_fp8_sdwa v[120:121], v116 src0_sel:WORD_1
	v_pk_fma_f32 v[118:119], v[122:123], v[208:209], v[118:119]
	v_cvt_pk_f32_fp8_e32 v[122:123], v117
	v_pk_fma_f32 v[114:115], v[114:115], v[144:145], v[118:119]
	v_cvt_pk_f32_fp8_e32 v[118:119], v116
	v_cvt_pk_f32_fp8_sdwa v[116:117], v117 src0_sel:WORD_1
	v_pk_fma_f32 v[114:115], v[118:119], v[202:203], v[114:115]
	s_nop 0
	v_pk_fma_f32 v[114:115], v[120:121], v[138:139], v[114:115]
	v_cvt_pk_f32_fp8_e32 v[118:119], v111
	v_pk_fma_f32 v[114:115], v[122:123], v[142:143], v[114:115]
	s_nop 0
	v_pk_fma_f32 v[114:115], v[116:117], v[140:141], v[114:115]
	v_cvt_pk_f32_fp8_sdwa v[116:117], v110 src0_sel:WORD_1
	v_add_f32_e32 v120, v114, v115
	v_cvt_pk_f32_fp8_e32 v[114:115], v110
	v_cvt_pk_f32_fp8_sdwa v[110:111], v111 src0_sel:WORD_1
	v_pk_fma_f32 v[114:115], v[114:115], v[204:205], 0 op_sel_hi:[1,1,0]
	s_nop 0
	v_pk_fma_f32 v[114:115], v[116:117], v[206:207], v[114:115]
	v_cvt_pk_f32_fp8_sdwa v[116:117], v112 src0_sel:WORD_1
	v_pk_fma_f32 v[114:115], v[118:119], v[208:209], v[114:115]
	v_cvt_pk_f32_fp8_e32 v[118:119], v113
	v_pk_fma_f32 v[110:111], v[110:111], v[144:145], v[114:115]
	v_cvt_pk_f32_fp8_e32 v[114:115], v112
	v_cvt_pk_f32_fp8_sdwa v[112:113], v113 src0_sel:WORD_1
	v_pk_fma_f32 v[110:111], v[114:115], v[202:203], v[110:111]
	s_nop 0
	v_pk_fma_f32 v[110:111], v[116:117], v[138:139], v[110:111]
	v_cvt_pk_f32_fp8_e32 v[114:115], v107
	v_pk_fma_f32 v[110:111], v[118:119], v[142:143], v[110:111]
	s_nop 0
	v_pk_fma_f32 v[110:111], v[112:113], v[140:141], v[110:111]
	v_cvt_pk_f32_fp8_sdwa v[112:113], v106 src0_sel:WORD_1
	v_add_f32_e32 v116, v110, v111
	v_cvt_pk_f32_fp8_e32 v[110:111], v106
	v_cvt_pk_f32_fp8_sdwa v[106:107], v107 src0_sel:WORD_1
	v_pk_fma_f32 v[110:111], v[110:111], v[204:205], 0 op_sel_hi:[1,1,0]
	s_nop 0
	v_pk_fma_f32 v[110:111], v[112:113], v[206:207], v[110:111]
	v_cvt_pk_f32_fp8_sdwa v[112:113], v108 src0_sel:WORD_1
	v_pk_fma_f32 v[110:111], v[114:115], v[208:209], v[110:111]
	v_cvt_pk_f32_fp8_e32 v[114:115], v109
	v_pk_fma_f32 v[106:107], v[106:107], v[144:145], v[110:111]
	v_cvt_pk_f32_fp8_e32 v[110:111], v108
	v_cvt_pk_f32_fp8_sdwa v[108:109], v109 src0_sel:WORD_1
	v_pk_fma_f32 v[106:107], v[110:111], v[202:203], v[106:107]
	s_nop 0
	v_pk_fma_f32 v[106:107], v[112:113], v[138:139], v[106:107]
	v_cvt_pk_f32_fp8_e32 v[110:111], v103
	v_pk_fma_f32 v[106:107], v[114:115], v[142:143], v[106:107]
	s_nop 0
	v_pk_fma_f32 v[106:107], v[108:109], v[140:141], v[106:107]
	v_cvt_pk_f32_fp8_sdwa v[108:109], v102 src0_sel:WORD_1
	v_add_f32_e32 v112, v106, v107
	v_cvt_pk_f32_fp8_e32 v[106:107], v102
	v_cvt_pk_f32_fp8_sdwa v[102:103], v103 src0_sel:WORD_1
	v_pk_fma_f32 v[106:107], v[106:107], v[204:205], 0 op_sel_hi:[1,1,0]
	s_nop 0
	v_pk_fma_f32 v[106:107], v[108:109], v[206:207], v[106:107]
	v_cvt_pk_f32_fp8_sdwa v[108:109], v104 src0_sel:WORD_1
	v_pk_fma_f32 v[106:107], v[110:111], v[208:209], v[106:107]
	v_cvt_pk_f32_fp8_e32 v[110:111], v105
	v_pk_fma_f32 v[102:103], v[102:103], v[144:145], v[106:107]
	v_cvt_pk_f32_fp8_e32 v[106:107], v104
	v_cvt_pk_f32_fp8_sdwa v[104:105], v105 src0_sel:WORD_1
	v_pk_fma_f32 v[102:103], v[106:107], v[202:203], v[102:103]
	s_nop 0
	v_pk_fma_f32 v[102:103], v[108:109], v[138:139], v[102:103]
	v_cvt_pk_f32_fp8_e32 v[106:107], v99
	v_pk_fma_f32 v[102:103], v[110:111], v[142:143], v[102:103]
	s_nop 0
	v_pk_fma_f32 v[102:103], v[104:105], v[140:141], v[102:103]
	v_cvt_pk_f32_fp8_sdwa v[104:105], v98 src0_sel:WORD_1
	v_add_f32_e32 v108, v102, v103
	v_cvt_pk_f32_fp8_e32 v[102:103], v98
	v_cvt_pk_f32_fp8_sdwa v[98:99], v99 src0_sel:WORD_1
	v_pk_fma_f32 v[102:103], v[102:103], v[204:205], 0 op_sel_hi:[1,1,0]
	s_nop 0
	v_pk_fma_f32 v[102:103], v[104:105], v[206:207], v[102:103]
	v_cvt_pk_f32_fp8_sdwa v[104:105], v100 src0_sel:WORD_1
	v_pk_fma_f32 v[102:103], v[106:107], v[208:209], v[102:103]
	v_cvt_pk_f32_fp8_e32 v[106:107], v101
	v_pk_fma_f32 v[98:99], v[98:99], v[144:145], v[102:103]
	v_cvt_pk_f32_fp8_e32 v[102:103], v100
	v_cvt_pk_f32_fp8_sdwa v[100:101], v101 src0_sel:WORD_1
	v_pk_fma_f32 v[98:99], v[102:103], v[202:203], v[98:99]
	s_nop 0
	v_pk_fma_f32 v[98:99], v[104:105], v[138:139], v[98:99]
	v_cvt_pk_f32_fp8_e32 v[102:103], v95
	v_pk_fma_f32 v[98:99], v[106:107], v[142:143], v[98:99]
	s_nop 0
	v_pk_fma_f32 v[98:99], v[100:101], v[140:141], v[98:99]
	v_cvt_pk_f32_fp8_sdwa v[100:101], v94 src0_sel:WORD_1
	v_add_f32_e32 v104, v98, v99
	v_cvt_pk_f32_fp8_e32 v[98:99], v94
	v_cvt_pk_f32_fp8_sdwa v[94:95], v95 src0_sel:WORD_1
	v_pk_fma_f32 v[98:99], v[98:99], v[204:205], 0 op_sel_hi:[1,1,0]
	s_nop 0
	v_pk_fma_f32 v[98:99], v[100:101], v[206:207], v[98:99]
	v_cvt_pk_f32_fp8_sdwa v[100:101], v96 src0_sel:WORD_1
	v_pk_fma_f32 v[98:99], v[102:103], v[208:209], v[98:99]
	v_cvt_pk_f32_fp8_e32 v[102:103], v97
	v_pk_fma_f32 v[94:95], v[94:95], v[144:145], v[98:99]
	v_cvt_pk_f32_fp8_e32 v[98:99], v96
	v_cvt_pk_f32_fp8_sdwa v[96:97], v97 src0_sel:WORD_1
	v_pk_fma_f32 v[94:95], v[98:99], v[202:203], v[94:95]
	s_nop 0
	v_pk_fma_f32 v[94:95], v[100:101], v[138:139], v[94:95]
	v_cvt_pk_f32_fp8_e32 v[98:99], v91
	v_pk_fma_f32 v[94:95], v[102:103], v[142:143], v[94:95]
	s_nop 0
	v_pk_fma_f32 v[94:95], v[96:97], v[140:141], v[94:95]
	v_cvt_pk_f32_fp8_sdwa v[96:97], v90 src0_sel:WORD_1
	v_add_f32_e32 v100, v94, v95
	v_cvt_pk_f32_fp8_e32 v[94:95], v90
	v_cvt_pk_f32_fp8_sdwa v[90:91], v91 src0_sel:WORD_1
	v_pk_fma_f32 v[94:95], v[94:95], v[204:205], 0 op_sel_hi:[1,1,0]
	s_nop 0
	v_pk_fma_f32 v[94:95], v[96:97], v[206:207], v[94:95]
	v_cvt_pk_f32_fp8_sdwa v[96:97], v92 src0_sel:WORD_1
	v_pk_fma_f32 v[94:95], v[98:99], v[208:209], v[94:95]
	v_cvt_pk_f32_fp8_e32 v[98:99], v93
; DI void dn2_math(const u32x4 (&W)[16], u32x4 x0, u32x4 x1, float* __restrict__ parow, int lane) {
;     ...
;   for (int j = 0; j < 16; ++j) {
;     f2 s2 = {0.f, 0.f};
; #pragma unroll
;     for (int d = 0; d < 4; ++d) {
;       f2 lo = __builtin_amdgcn_cvt_pk_f32_fp8((int)W[j][d], false);
;       f2 hi = __builtin_amdgcn_cvt_pk_f32_fp8((int)W[j][d], true);
;       s2 = lo * xf[2 * d] + s2;
;       s2 = hi * xf[2 * d + 1] + s2;
;     }
;     pv[j] = s2.x + s2.y;
;   }
;   const bool b2 = lane & 4, b1 = lane & 2, b0 = lane & 1;
;   float q8[8];
; #pragma unroll
;   for (int i = 0; i < 8; ++i) { float snd = b2 ? pv[i] : pv[i + 8]; float kp = b2 ? pv[i + 8] : pv[i]; q8[i] = kp + __shfl_xor(snd, 4); }
;   float q4[4];
; #pragma unroll
;   for (int i = 0; i < 4; ++i) { float snd = b1 ? q8[i] : q8[i + 4]; float kp = b1 ? q8[i + 4] : q8[i]; q4[i] = kp + __shfl_xor(snd, 2); }
;   float r2[2];
; #pragma unroll
;   for (int i = 0; i < 2; ++i) { float snd = b0 ? q4[i] : q4[i + 2]; float kp = b0 ? q4[i + 2] : q4[i]; r2[i] = kp + __shfl_xor(snd, 1); }
;   const int j0 = (b0 ? 2 : 0) + (b1 ? 4 : 0) + (b2 ? 8 : 0);
;   const int grp = lane >> 3;
;   parow[8 * j0 + grp] = r2[0];
;   parow[8 * (j0 + 1) + grp] = r2[1];
	v_pk_fma_f32 v[90:91], v[90:91], v[144:145], v[94:95]
	v_cvt_pk_f32_fp8_e32 v[94:95], v92
	v_cvt_pk_f32_fp8_sdwa v[92:93], v93 src0_sel:WORD_1
	v_pk_fma_f32 v[90:91], v[94:95], v[202:203], v[90:91]
	s_nop 0
	v_pk_fma_f32 v[90:91], v[96:97], v[138:139], v[90:91]
	v_cvt_pk_f32_fp8_e32 v[94:95], v87
	v_pk_fma_f32 v[90:91], v[98:99], v[142:143], v[90:91]
	s_nop 0
	v_pk_fma_f32 v[90:91], v[92:93], v[140:141], v[90:91]
	v_cvt_pk_f32_fp8_sdwa v[92:93], v86 src0_sel:WORD_1
	v_add_f32_e32 v96, v90, v91
	v_cvt_pk_f32_fp8_e32 v[90:91], v86
	v_cvt_pk_f32_fp8_sdwa v[86:87], v87 src0_sel:WORD_1
	v_pk_fma_f32 v[90:91], v[90:91], v[204:205], 0 op_sel_hi:[1,1,0]
	s_nop 0
	v_pk_fma_f32 v[90:91], v[92:93], v[206:207], v[90:91]
	v_cvt_pk_f32_fp8_sdwa v[92:93], v88 src0_sel:WORD_1
	v_pk_fma_f32 v[90:91], v[94:95], v[208:209], v[90:91]
	v_cvt_pk_f32_fp8_e32 v[94:95], v89
	v_pk_fma_f32 v[86:87], v[86:87], v[144:145], v[90:91]
	v_cvt_pk_f32_fp8_e32 v[90:91], v88
	v_cvt_pk_f32_fp8_sdwa v[88:89], v89 src0_sel:WORD_1
	v_pk_fma_f32 v[86:87], v[90:91], v[202:203], v[86:87]
	s_nop 0
	v_pk_fma_f32 v[86:87], v[92:93], v[138:139], v[86:87]
	v_cvt_pk_f32_fp8_e32 v[90:91], v83
	v_pk_fma_f32 v[86:87], v[94:95], v[142:143], v[86:87]
	s_nop 0
	v_pk_fma_f32 v[86:87], v[88:89], v[140:141], v[86:87]
	v_cvt_pk_f32_fp8_sdwa v[88:89], v82 src0_sel:WORD_1
	v_add_f32_e32 v92, v86, v87
	v_cvt_pk_f32_fp8_e32 v[86:87], v82
	v_cvt_pk_f32_fp8_sdwa v[82:83], v83 src0_sel:WORD_1
	v_pk_fma_f32 v[86:87], v[86:87], v[204:205], 0 op_sel_hi:[1,1,0]
	s_nop 0
	v_pk_fma_f32 v[86:87], v[88:89], v[206:207], v[86:87]
	v_cvt_pk_f32_fp8_sdwa v[88:89], v84 src0_sel:WORD_1
	v_pk_fma_f32 v[86:87], v[90:91], v[208:209], v[86:87]
	v_cvt_pk_f32_fp8_e32 v[90:91], v85
	v_pk_fma_f32 v[82:83], v[82:83], v[144:145], v[86:87]
	v_cvt_pk_f32_fp8_e32 v[86:87], v84
	v_cvt_pk_f32_fp8_sdwa v[84:85], v85 src0_sel:WORD_1
	v_pk_fma_f32 v[82:83], v[86:87], v[202:203], v[82:83]
	s_nop 0
	v_pk_fma_f32 v[82:83], v[88:89], v[138:139], v[82:83]
	v_cvt_pk_f32_fp8_e32 v[86:87], v79
	v_pk_fma_f32 v[82:83], v[90:91], v[142:143], v[82:83]
	s_nop 0
	v_pk_fma_f32 v[82:83], v[84:85], v[140:141], v[82:83]
	v_cvt_pk_f32_fp8_sdwa v[84:85], v78 src0_sel:WORD_1
	v_add_f32_e32 v88, v82, v83
	v_cvt_pk_f32_fp8_e32 v[82:83], v78
	v_cvt_pk_f32_fp8_sdwa v[78:79], v79 src0_sel:WORD_1
	v_pk_fma_f32 v[82:83], v[82:83], v[204:205], 0 op_sel_hi:[1,1,0]
	s_nop 0
	v_pk_fma_f32 v[82:83], v[84:85], v[206:207], v[82:83]
	v_cvt_pk_f32_fp8_sdwa v[84:85], v80 src0_sel:WORD_1
	v_pk_fma_f32 v[82:83], v[86:87], v[208:209], v[82:83]
	v_cvt_pk_f32_fp8_e32 v[86:87], v81
	v_pk_fma_f32 v[78:79], v[78:79], v[144:145], v[82:83]
	v_cvt_pk_f32_fp8_e32 v[82:83], v80
	v_cvt_pk_f32_fp8_sdwa v[80:81], v81 src0_sel:WORD_1
	v_pk_fma_f32 v[78:79], v[82:83], v[202:203], v[78:79]
	s_nop 0
	v_pk_fma_f32 v[78:79], v[84:85], v[138:139], v[78:79]
	v_cvt_pk_f32_fp8_e32 v[82:83], v75
	v_pk_fma_f32 v[78:79], v[86:87], v[142:143], v[78:79]
	s_nop 0
	v_pk_fma_f32 v[78:79], v[80:81], v[140:141], v[78:79]
	v_cvt_pk_f32_fp8_sdwa v[80:81], v74 src0_sel:WORD_1
	v_add_f32_e32 v84, v78, v79
	v_cvt_pk_f32_fp8_e32 v[78:79], v74
	v_cvt_pk_f32_fp8_sdwa v[74:75], v75 src0_sel:WORD_1
	v_pk_fma_f32 v[78:79], v[78:79], v[204:205], 0 op_sel_hi:[1,1,0]
	s_nop 0
	v_pk_fma_f32 v[78:79], v[80:81], v[206:207], v[78:79]
	v_cvt_pk_f32_fp8_sdwa v[80:81], v76 src0_sel:WORD_1
	v_pk_fma_f32 v[78:79], v[82:83], v[208:209], v[78:79]
	v_cvt_pk_f32_fp8_e32 v[82:83], v77
	v_pk_fma_f32 v[74:75], v[74:75], v[144:145], v[78:79]
	v_cvt_pk_f32_fp8_e32 v[78:79], v76
	v_cvt_pk_f32_fp8_sdwa v[76:77], v77 src0_sel:WORD_1
	v_pk_fma_f32 v[74:75], v[78:79], v[202:203], v[74:75]
	s_nop 0
	v_pk_fma_f32 v[74:75], v[80:81], v[138:139], v[74:75]
	v_pk_fma_f32 v[74:75], v[82:83], v[142:143], v[74:75]
	v_pk_fma_f32 v[74:75], v[76:77], v[140:141], v[74:75]
	v_add_f32_e32 v74, v74, v75
	s_nop 1
	v_add_f32_dpp v74, v74, v74 row_shr:4 row_mask:0xf bank_mask:0xa
	v_add_f32_dpp v75, v167, v167 row_shl:4 row_mask:0xf bank_mask:0x5
	v_add_f32_dpp v76, v136, v136 row_shl:4 row_mask:0xf bank_mask:0x5
	v_add_f32_dpp v77, v132, v132 row_shl:4 row_mask:0xf bank_mask:0x5
	v_add_f32_dpp v78, v128, v128 row_shl:4 row_mask:0xf bank_mask:0x5
	v_add_f32_dpp v79, v124, v124 row_shl:4 row_mask:0xf bank_mask:0x5
	v_add_f32_dpp v80, v120, v120 row_shl:4 row_mask:0xf bank_mask:0x5
	v_add_f32_dpp v81, v116, v116 row_shl:4 row_mask:0xf bank_mask:0x5
	v_add_f32_dpp v74, v112, v112 row_shl:4 row_mask:0xf bank_mask:0x5
	v_add_f32_dpp v75, v108, v108 row_shr:4 row_mask:0xf bank_mask:0xa
	v_add_f32_dpp v76, v104, v104 row_shr:4 row_mask:0xf bank_mask:0xa
	v_add_f32_dpp v77, v100, v100 row_shr:4 row_mask:0xf bank_mask:0xa
	v_add_f32_dpp v78, v96, v96 row_shr:4 row_mask:0xf bank_mask:0xa
	v_add_f32_dpp v79, v92, v92 row_shr:4 row_mask:0xf bank_mask:0xa
	v_add_f32_dpp v80, v88, v88 row_shr:4 row_mask:0xf bank_mask:0xa
	v_add_f32_dpp v81, v84, v84 row_shr:4 row_mask:0xf bank_mask:0xa
	s_nop 1
	v_add_f32_dpp v75, v75, v75 quad_perm:[2,3,0,1] row_mask:0xf bank_mask:0xf
	v_add_f32_dpp v77, v77, v77 quad_perm:[2,3,0,1] row_mask:0xf bank_mask:0xf
	v_add_f32_dpp v76, v76, v76 quad_perm:[2,3,0,1] row_mask:0xf bank_mask:0xf
	v_add_f32_dpp v78, v78, v78 quad_perm:[2,3,0,1] row_mask:0xf bank_mask:0xf
	v_add_f32_dpp v79, v79, v79 quad_perm:[2,3,0,1] row_mask:0xf bank_mask:0xf
	v_add_f32_dpp v81, v81, v81 quad_perm:[2,3,0,1] row_mask:0xf bank_mask:0xf
	v_add_f32_dpp v80, v80, v80 quad_perm:[2,3,0,1] row_mask:0xf bank_mask:0xf
	v_add_f32_dpp v74, v74, v74 quad_perm:[2,3,0,1] row_mask:0xf bank_mask:0xf
	v_cndmask_b32_e64 v75, v79, v75, s[10:11]
	v_cndmask_b32_e64 v77, v81, v77, s[10:11]
	v_cndmask_b32_e64 v76, v80, v76, s[10:11]
	v_cndmask_b32_e64 v74, v74, v78, s[10:11]
	s_nop 1
	v_add_f32_dpp v75, v75, v75 quad_perm:[1,0,3,2] row_mask:0xf bank_mask:0xf
	v_add_f32_dpp v76, v76, v76 quad_perm:[1,0,3,2] row_mask:0xf bank_mask:0xf
	v_add_f32_dpp v77, v77, v77 quad_perm:[1,0,3,2] row_mask:0xf bank_mask:0xf
	v_add_f32_dpp v74, v74, v74 quad_perm:[1,0,3,2] row_mask:0xf bank_mask:0xf
	v_cndmask_b32_e64 v75, v77, v75, s[12:13]
	v_cndmask_b32_e64 v74, v74, v76, s[12:13]
	global_store_dword v[200:201], v75, off
	global_store_dword v[200:201], v74, off offset:32
	v_lshl_add_u64 v[198:199], v[198:199], 0, s[20:21]
	v_add_u32_e32 v165, 0x400, v165
	v_lshl_add_u64 v[200:201], v[200:201], 0, s[36:37]
	s_and_b64 vcc, exec, s[28:29]
	s_cbranch_vccnz .LBB0_1504
; DI float bflo(u32 u) { return __uint_as_float(u << 16); }
; DI float bfhi(u32 u) { return __uint_as_float(u & 0xffff0000u); }
; DI void dn2_issue(u32x4 (&W)[16], const int* pl, const unsigned char* wbase, int grp) {
; #pragma unroll
;   for (int j = 0; j < 16; ++j) W[j] = *(const u32x4*)(wbase + (size_t)pl[8 * j + grp] * 1024);
; }
; DI void dn2_math(const u32x4 (&W)[16], u32x4 x0, u32x4 x1, float* __restrict__ parow, int lane) {
;   f2 xf[8];
; #pragma unroll
;   for (int q = 0; q < 4; ++q) { xf[q] = f2{bflo(x0[q]), bfhi(x0[q])}; xf[4 + q] = f2{bflo(x1[q]), bfhi(x1[q])}; }
;   float pv[16];
; #pragma unroll
;   for (int j = 0; j < 16; ++j) {
;     f2 s2 = {0.f, 0.f};
; #pragma unroll
;     for (int d = 0; d < 4; ++d) {
;       f2 lo = __builtin_amdgcn_cvt_pk_f32_fp8((int)W[j][d], false);
;       f2 hi = __builtin_amdgcn_cvt_pk_f32_fp8((int)W[j][d], true);
;       s2 = lo * xf[2 * d] + s2;
;       s2 = hi * xf[2 * d + 1] + s2;
;     }
;     pv[j] = s2.x + s2.y;
.LBB0_1517:
	ds_read2_b32 v[134:135], v165 offset1:8
	ds_read2_b32 v[126:127], v165 offset0:16 offset1:24
	ds_read2_b32 v[118:119], v165 offset0:32 offset1:40
	ds_read2_b32 v[110:111], v165 offset0:48 offset1:56
	ds_read2_b32 v[102:103], v165 offset0:64 offset1:72
	ds_read2_b32 v[94:95], v165 offset0:80 offset1:88
	ds_read2_b32 v[86:87], v165 offset0:96 offset1:104
	ds_read2_b32 v[78:79], v165 offset0:112 offset1:120
	s_waitcnt lgkmcnt(7)
	v_lshl_add_u32 v130, v135, 10, v250
	v_lshl_add_u32 v134, v134, 10, v250
	global_load_dwordx4 v[134:137], v134, s[98:99]
	global_load_dwordx4 v[130:133], v130, s[98:99]
	s_waitcnt lgkmcnt(6)
	v_lshl_add_u32 v122, v127, 10, v250
	v_lshl_add_u32 v126, v126, 10, v250
	global_load_dwordx4 v[126:129], v126, s[98:99]
	global_load_dwordx4 v[122:125], v122, s[98:99]
	s_waitcnt lgkmcnt(5)
	v_lshl_add_u32 v114, v119, 10, v250
	v_lshl_add_u32 v118, v118, 10, v250
	global_load_dwordx4 v[118:121], v118, s[98:99]
	global_load_dwordx4 v[114:117], v114, s[98:99]
	s_waitcnt lgkmcnt(4)
	v_lshl_add_u32 v106, v111, 10, v250
	v_lshl_add_u32 v110, v110, 10, v250
	global_load_dwordx4 v[110:113], v110, s[98:99]
	global_load_dwordx4 v[106:109], v106, s[98:99]
	s_waitcnt lgkmcnt(3)
	v_lshl_add_u32 v98, v103, 10, v250
	v_lshl_add_u32 v102, v102, 10, v250
	global_load_dwordx4 v[102:105], v102, s[98:99]
	global_load_dwordx4 v[98:101], v98, s[98:99]
	s_waitcnt lgkmcnt(2)
	v_lshl_add_u32 v90, v95, 10, v250
	v_lshl_add_u32 v94, v94, 10, v250
	global_load_dwordx4 v[94:97], v94, s[98:99]
	global_load_dwordx4 v[90:93], v90, s[98:99]
	s_waitcnt lgkmcnt(1)
	v_lshl_add_u32 v82, v87, 10, v250
	v_lshl_add_u32 v86, v86, 10, v250
	global_load_dwordx4 v[86:89], v86, s[98:99]
	global_load_dwordx4 v[82:85], v82, s[98:99]
	s_waitcnt lgkmcnt(0)
	v_lshl_add_u32 v74, v79, 10, v250
	v_lshl_add_u32 v78, v78, 10, v250
	global_load_dwordx4 v[78:81], v78, s[98:99]
	global_load_dwordx4 v[74:77], v74, s[98:99]
	s_nop 0
	global_load_dwordx4 v[138:141], v[198:199], off offset:-2032
	global_load_dwordx4 v[142:145], v[198:199], off offset:-2048
	s_waitcnt vmcnt(35)
	v_cvt_pk_f32_fp8_e32 v[230:231], v2
	v_cvt_pk_f32_fp8_sdwa v[232:233], v2 src0_sel:WORD_1
	v_cvt_pk_f32_fp8_e32 v[234:235], v3
	s_waitcnt vmcnt(18)
	v_lshlrev_b32_e32 v210, 16, v70
	v_and_b32_e32 v211, 0xffff0000, v70
	v_cvt_pk_f32_fp8_sdwa v[236:237], v3 src0_sel:WORD_1
	v_lshlrev_b32_e32 v212, 16, v71
	v_and_b32_e32 v213, 0xffff0000, v71
	v_pk_fma_f32 v[230:231], v[230:231], v[210:211], 0 op_sel_hi:[1,1,0]
	v_lshlrev_b32_e32 v214, 16, v72
	v_and_b32_e32 v215, 0xffff0000, v72
	v_pk_fma_f32 v[230:231], v[232:233], v[212:213], v[230:231]
	v_cvt_pk_f32_fp8_e32 v[232:233], v4
	v_lshlrev_b32_e32 v216, 16, v73
	v_and_b32_e32 v217, 0xffff0000, v73
	v_pk_fma_f32 v[230:231], v[234:235], v[214:215], v[230:231]
	v_cvt_pk_f32_fp8_sdwa v[234:235], v4 src0_sel:WORD_1
	v_pk_fma_f32 v[230:231], v[236:237], v[216:217], v[230:231]
	v_cvt_pk_f32_fp8_e32 v[236:237], v5
	v_lshlrev_b32_e32 v202, 16, v66
	v_and_b32_e32 v203, 0xffff0000, v66
	v_cvt_pk_f32_fp8_sdwa v[238:239], v5 src0_sel:WORD_1
	v_lshlrev_b32_e32 v204, 16, v67
	v_and_b32_e32 v205, 0xffff0000, v67
	v_pk_fma_f32 v[230:231], v[232:233], v[202:203], v[230:231]
	v_lshlrev_b32_e32 v206, 16, v68
	v_and_b32_e32 v207, 0xffff0000, v68
	v_pk_fma_f32 v[230:231], v[234:235], v[204:205], v[230:231]
	v_lshlrev_b32_e32 v208, 16, v69
	v_and_b32_e32 v209, 0xffff0000, v69
	v_pk_fma_f32 v[230:231], v[236:237], v[206:207], v[230:231]
	v_cvt_pk_f32_fp8_sdwa v[232:233], v6 src0_sel:WORD_1
	v_pk_fma_f32 v[230:231], v[238:239], v[208:209], v[230:231]
	v_cvt_pk_f32_fp8_e32 v[234:235], v7
	v_add_f32_e32 v167, v230, v231
	v_cvt_pk_f32_fp8_e32 v[230:231], v6
	v_cvt_pk_f32_fp8_sdwa v[236:237], v7 src0_sel:WORD_1
	v_cvt_pk_f32_fp8_sdwa v[238:239], v9 src0_sel:WORD_1
	v_pk_fma_f32 v[230:231], v[230:231], v[210:211], 0 op_sel_hi:[1,1,0]
	s_nop 0
	v_pk_fma_f32 v[230:231], v[232:233], v[212:213], v[230:231]
	v_cvt_pk_f32_fp8_e32 v[232:233], v8
	v_pk_fma_f32 v[230:231], v[234:235], v[214:215], v[230:231]
	v_cvt_pk_f32_fp8_sdwa v[234:235], v8 src0_sel:WORD_1
	v_pk_fma_f32 v[230:231], v[236:237], v[216:217], v[230:231]
	v_cvt_pk_f32_fp8_e32 v[236:237], v9
	v_pk_fma_f32 v[230:231], v[232:233], v[202:203], v[230:231]
	v_cvt_pk_f32_fp8_sdwa v[232:233], v10 src0_sel:WORD_1
	v_pk_fma_f32 v[230:231], v[234:235], v[204:205], v[230:231]
	v_cvt_pk_f32_fp8_e32 v[234:235], v11
	v_pk_fma_f32 v[230:231], v[236:237], v[206:207], v[230:231]
	v_cvt_pk_f32_fp8_sdwa v[236:237], v11 src0_sel:WORD_1
	v_pk_fma_f32 v[230:231], v[238:239], v[208:209], v[230:231]
	v_cvt_pk_f32_fp8_sdwa v[238:239], v13 src0_sel:WORD_1
	v_add_f32_e32 v169, v230, v231
	v_cvt_pk_f32_fp8_e32 v[230:231], v10
	v_pk_fma_f32 v[230:231], v[230:231], v[210:211], 0 op_sel_hi:[1,1,0]
	s_nop 0
	v_pk_fma_f32 v[230:231], v[232:233], v[212:213], v[230:231]
	v_cvt_pk_f32_fp8_e32 v[232:233], v12
	v_pk_fma_f32 v[230:231], v[234:235], v[214:215], v[230:231]
	v_cvt_pk_f32_fp8_sdwa v[234:235], v12 src0_sel:WORD_1
	v_pk_fma_f32 v[230:231], v[236:237], v[216:217], v[230:231]
	v_cvt_pk_f32_fp8_e32 v[236:237], v13
	v_pk_fma_f32 v[230:231], v[232:233], v[202:203], v[230:231]
	v_cvt_pk_f32_fp8_sdwa v[232:233], v14 src0_sel:WORD_1
	v_pk_fma_f32 v[230:231], v[234:235], v[204:205], v[230:231]
	v_cvt_pk_f32_fp8_e32 v[234:235], v15
	v_pk_fma_f32 v[230:231], v[236:237], v[206:207], v[230:231]
	v_cvt_pk_f32_fp8_sdwa v[236:237], v15 src0_sel:WORD_1
	v_pk_fma_f32 v[230:231], v[238:239], v[208:209], v[230:231]
	v_cvt_pk_f32_fp8_sdwa v[238:239], v17 src0_sel:WORD_1
	v_add_f32_e32 v171, v230, v231
	v_cvt_pk_f32_fp8_e32 v[230:231], v14
; DI void dn2_math(const u32x4 (&W)[16], u32x4 x0, u32x4 x1, float* __restrict__ parow, int lane) {
;     ...
;   for (int j = 0; j < 16; ++j) {
;     f2 s2 = {0.f, 0.f};
; #pragma unroll
;     for (int d = 0; d < 4; ++d) {
;       f2 lo = __builtin_amdgcn_cvt_pk_f32_fp8((int)W[j][d], false);
;       f2 hi = __builtin_amdgcn_cvt_pk_f32_fp8((int)W[j][d], true);
;       s2 = lo * xf[2 * d] + s2;
;       s2 = hi * xf[2 * d + 1] + s2;
;     }
;     pv[j] = s2.x + s2.y;
	v_pk_fma_f32 v[230:231], v[230:231], v[210:211], 0 op_sel_hi:[1,1,0]
	s_nop 0
	v_pk_fma_f32 v[230:231], v[232:233], v[212:213], v[230:231]
	v_cvt_pk_f32_fp8_e32 v[232:233], v16
	v_pk_fma_f32 v[230:231], v[234:235], v[214:215], v[230:231]
	v_cvt_pk_f32_fp8_sdwa v[234:235], v16 src0_sel:WORD_1
	v_pk_fma_f32 v[230:231], v[236:237], v[216:217], v[230:231]
	v_cvt_pk_f32_fp8_e32 v[236:237], v17
	v_pk_fma_f32 v[230:231], v[232:233], v[202:203], v[230:231]
	v_cvt_pk_f32_fp8_sdwa v[232:233], v18 src0_sel:WORD_1
	v_pk_fma_f32 v[230:231], v[234:235], v[204:205], v[230:231]
	v_cvt_pk_f32_fp8_e32 v[234:235], v19
	v_pk_fma_f32 v[230:231], v[236:237], v[206:207], v[230:231]
	v_cvt_pk_f32_fp8_sdwa v[236:237], v19 src0_sel:WORD_1
	v_pk_fma_f32 v[230:231], v[238:239], v[208:209], v[230:231]
	v_cvt_pk_f32_fp8_sdwa v[238:239], v21 src0_sel:WORD_1
	v_add_f32_e32 v173, v230, v231
	v_cvt_pk_f32_fp8_e32 v[230:231], v18
	v_pk_fma_f32 v[230:231], v[230:231], v[210:211], 0 op_sel_hi:[1,1,0]
	s_nop 0
	v_pk_fma_f32 v[230:231], v[232:233], v[212:213], v[230:231]
	v_cvt_pk_f32_fp8_e32 v[232:233], v20
	v_pk_fma_f32 v[230:231], v[234:235], v[214:215], v[230:231]
	v_cvt_pk_f32_fp8_sdwa v[234:235], v20 src0_sel:WORD_1
	v_pk_fma_f32 v[230:231], v[236:237], v[216:217], v[230:231]
	v_cvt_pk_f32_fp8_e32 v[236:237], v21
	v_pk_fma_f32 v[230:231], v[232:233], v[202:203], v[230:231]
	v_cvt_pk_f32_fp8_sdwa v[232:233], v22 src0_sel:WORD_1
	v_pk_fma_f32 v[230:231], v[234:235], v[204:205], v[230:231]
	v_cvt_pk_f32_fp8_e32 v[234:235], v23
	v_pk_fma_f32 v[230:231], v[236:237], v[206:207], v[230:231]
	v_cvt_pk_f32_fp8_sdwa v[236:237], v23 src0_sel:WORD_1
	v_pk_fma_f32 v[230:231], v[238:239], v[208:209], v[230:231]
	v_cvt_pk_f32_fp8_sdwa v[238:239], v25 src0_sel:WORD_1
	v_add_f32_e32 v175, v230, v231
	v_cvt_pk_f32_fp8_e32 v[230:231], v22
	v_pk_fma_f32 v[230:231], v[230:231], v[210:211], 0 op_sel_hi:[1,1,0]
	s_nop 0
	v_pk_fma_f32 v[230:231], v[232:233], v[212:213], v[230:231]
	v_cvt_pk_f32_fp8_e32 v[232:233], v24
	v_pk_fma_f32 v[230:231], v[234:235], v[214:215], v[230:231]
	v_cvt_pk_f32_fp8_sdwa v[234:235], v24 src0_sel:WORD_1
	v_pk_fma_f32 v[230:231], v[236:237], v[216:217], v[230:231]
	v_cvt_pk_f32_fp8_e32 v[236:237], v25
	v_pk_fma_f32 v[230:231], v[232:233], v[202:203], v[230:231]
	v_cvt_pk_f32_fp8_sdwa v[232:233], v26 src0_sel:WORD_1
	v_pk_fma_f32 v[230:231], v[234:235], v[204:205], v[230:231]
	v_cvt_pk_f32_fp8_e32 v[234:235], v27
	v_pk_fma_f32 v[230:231], v[236:237], v[206:207], v[230:231]
	v_cvt_pk_f32_fp8_sdwa v[236:237], v27 src0_sel:WORD_1
	v_pk_fma_f32 v[230:231], v[238:239], v[208:209], v[230:231]
	v_cvt_pk_f32_fp8_sdwa v[238:239], v29 src0_sel:WORD_1
	v_add_f32_e32 v177, v230, v231
	v_cvt_pk_f32_fp8_e32 v[230:231], v26
	v_pk_fma_f32 v[230:231], v[230:231], v[210:211], 0 op_sel_hi:[1,1,0]
	s_nop 0
	v_pk_fma_f32 v[230:231], v[232:233], v[212:213], v[230:231]
	v_cvt_pk_f32_fp8_e32 v[232:233], v28
	v_pk_fma_f32 v[230:231], v[234:235], v[214:215], v[230:231]
	v_cvt_pk_f32_fp8_sdwa v[234:235], v28 src0_sel:WORD_1
	v_pk_fma_f32 v[230:231], v[236:237], v[216:217], v[230:231]
	v_cvt_pk_f32_fp8_e32 v[236:237], v29
	v_pk_fma_f32 v[230:231], v[232:233], v[202:203], v[230:231]
	v_cvt_pk_f32_fp8_sdwa v[232:233], v30 src0_sel:WORD_1
	v_pk_fma_f32 v[230:231], v[234:235], v[204:205], v[230:231]
	v_cvt_pk_f32_fp8_e32 v[234:235], v31
	v_pk_fma_f32 v[230:231], v[236:237], v[206:207], v[230:231]
	v_cvt_pk_f32_fp8_sdwa v[236:237], v31 src0_sel:WORD_1
	v_pk_fma_f32 v[230:231], v[238:239], v[208:209], v[230:231]
	v_cvt_pk_f32_fp8_sdwa v[238:239], v33 src0_sel:WORD_1
	v_add_f32_e32 v179, v230, v231
	v_cvt_pk_f32_fp8_e32 v[230:231], v30
	v_pk_fma_f32 v[230:231], v[230:231], v[210:211], 0 op_sel_hi:[1,1,0]
	s_nop 0
	v_pk_fma_f32 v[230:231], v[232:233], v[212:213], v[230:231]
	v_cvt_pk_f32_fp8_e32 v[232:233], v32
	v_pk_fma_f32 v[230:231], v[234:235], v[214:215], v[230:231]
	v_cvt_pk_f32_fp8_sdwa v[234:235], v32 src0_sel:WORD_1
	v_pk_fma_f32 v[230:231], v[236:237], v[216:217], v[230:231]
	v_cvt_pk_f32_fp8_e32 v[236:237], v33
	v_pk_fma_f32 v[230:231], v[232:233], v[202:203], v[230:231]
	v_cvt_pk_f32_fp8_sdwa v[232:233], v34 src0_sel:WORD_1
	v_pk_fma_f32 v[230:231], v[234:235], v[204:205], v[230:231]
	v_cvt_pk_f32_fp8_e32 v[234:235], v35
	v_pk_fma_f32 v[230:231], v[236:237], v[206:207], v[230:231]
	v_cvt_pk_f32_fp8_sdwa v[236:237], v35 src0_sel:WORD_1
	v_pk_fma_f32 v[230:231], v[238:239], v[208:209], v[230:231]
	v_cvt_pk_f32_fp8_sdwa v[238:239], v37 src0_sel:WORD_1
	v_add_f32_e32 v181, v230, v231
	v_cvt_pk_f32_fp8_e32 v[230:231], v34
	v_pk_fma_f32 v[230:231], v[230:231], v[210:211], 0 op_sel_hi:[1,1,0]
	s_nop 0
	v_pk_fma_f32 v[230:231], v[232:233], v[212:213], v[230:231]
	v_cvt_pk_f32_fp8_e32 v[232:233], v36
	v_pk_fma_f32 v[230:231], v[234:235], v[214:215], v[230:231]
	v_cvt_pk_f32_fp8_sdwa v[234:235], v36 src0_sel:WORD_1
	v_pk_fma_f32 v[230:231], v[236:237], v[216:217], v[230:231]
	v_cvt_pk_f32_fp8_e32 v[236:237], v37
	v_pk_fma_f32 v[230:231], v[232:233], v[202:203], v[230:231]
	v_cvt_pk_f32_fp8_sdwa v[232:233], v38 src0_sel:WORD_1
	v_pk_fma_f32 v[230:231], v[234:235], v[204:205], v[230:231]
	v_cvt_pk_f32_fp8_e32 v[234:235], v39
	v_pk_fma_f32 v[230:231], v[236:237], v[206:207], v[230:231]
	v_cvt_pk_f32_fp8_sdwa v[236:237], v39 src0_sel:WORD_1
	v_pk_fma_f32 v[230:231], v[238:239], v[208:209], v[230:231]
	v_cvt_pk_f32_fp8_sdwa v[238:239], v41 src0_sel:WORD_1
	v_add_f32_e32 v183, v230, v231
	v_cvt_pk_f32_fp8_e32 v[230:231], v38
	v_pk_fma_f32 v[230:231], v[230:231], v[210:211], 0 op_sel_hi:[1,1,0]
	s_nop 0
	v_pk_fma_f32 v[230:231], v[232:233], v[212:213], v[230:231]
	v_cvt_pk_f32_fp8_e32 v[232:233], v40
; DI void dn2_math(const u32x4 (&W)[16], u32x4 x0, u32x4 x1, float* __restrict__ parow, int lane) {
;     ...
;   for (int j = 0; j < 16; ++j) {
;     f2 s2 = {0.f, 0.f};
; #pragma unroll
;     for (int d = 0; d < 4; ++d) {
;       f2 lo = __builtin_amdgcn_cvt_pk_f32_fp8((int)W[j][d], false);
;       f2 hi = __builtin_amdgcn_cvt_pk_f32_fp8((int)W[j][d], true);
;       s2 = lo * xf[2 * d] + s2;
;       s2 = hi * xf[2 * d + 1] + s2;
;     }
;     pv[j] = s2.x + s2.y;
	v_pk_fma_f32 v[230:231], v[234:235], v[214:215], v[230:231]
	v_cvt_pk_f32_fp8_sdwa v[234:235], v40 src0_sel:WORD_1
	v_pk_fma_f32 v[230:231], v[236:237], v[216:217], v[230:231]
	v_cvt_pk_f32_fp8_e32 v[236:237], v41
	v_pk_fma_f32 v[230:231], v[232:233], v[202:203], v[230:231]
	v_cvt_pk_f32_fp8_sdwa v[232:233], v42 src0_sel:WORD_1
	v_pk_fma_f32 v[230:231], v[234:235], v[204:205], v[230:231]
	v_cvt_pk_f32_fp8_e32 v[234:235], v43
	v_pk_fma_f32 v[230:231], v[236:237], v[206:207], v[230:231]
	v_cvt_pk_f32_fp8_sdwa v[236:237], v43 src0_sel:WORD_1
	v_pk_fma_f32 v[230:231], v[238:239], v[208:209], v[230:231]
	v_cvt_pk_f32_fp8_sdwa v[238:239], v45 src0_sel:WORD_1
	v_add_f32_e32 v185, v230, v231
	v_cvt_pk_f32_fp8_e32 v[230:231], v42
	v_pk_fma_f32 v[230:231], v[230:231], v[210:211], 0 op_sel_hi:[1,1,0]
	s_nop 0
	v_pk_fma_f32 v[230:231], v[232:233], v[212:213], v[230:231]
	v_cvt_pk_f32_fp8_e32 v[232:233], v44
	v_pk_fma_f32 v[230:231], v[234:235], v[214:215], v[230:231]
	v_cvt_pk_f32_fp8_sdwa v[234:235], v44 src0_sel:WORD_1
	v_pk_fma_f32 v[230:231], v[236:237], v[216:217], v[230:231]
	v_cvt_pk_f32_fp8_e32 v[236:237], v45
	v_pk_fma_f32 v[230:231], v[232:233], v[202:203], v[230:231]
	v_cvt_pk_f32_fp8_sdwa v[232:233], v46 src0_sel:WORD_1
	v_pk_fma_f32 v[230:231], v[234:235], v[204:205], v[230:231]
	v_cvt_pk_f32_fp8_e32 v[234:235], v47
	v_pk_fma_f32 v[230:231], v[236:237], v[206:207], v[230:231]
	v_cvt_pk_f32_fp8_sdwa v[236:237], v47 src0_sel:WORD_1
	v_pk_fma_f32 v[230:231], v[238:239], v[208:209], v[230:231]
	v_cvt_pk_f32_fp8_sdwa v[238:239], v49 src0_sel:WORD_1
	v_add_f32_e32 v187, v230, v231
	v_cvt_pk_f32_fp8_e32 v[230:231], v46
	v_pk_fma_f32 v[230:231], v[230:231], v[210:211], 0 op_sel_hi:[1,1,0]
	s_nop 0
	v_pk_fma_f32 v[230:231], v[232:233], v[212:213], v[230:231]
	v_cvt_pk_f32_fp8_e32 v[232:233], v48
	v_pk_fma_f32 v[230:231], v[234:235], v[214:215], v[230:231]
	v_cvt_pk_f32_fp8_sdwa v[234:235], v48 src0_sel:WORD_1
	v_pk_fma_f32 v[230:231], v[236:237], v[216:217], v[230:231]
	v_cvt_pk_f32_fp8_e32 v[236:237], v49
	v_pk_fma_f32 v[230:231], v[232:233], v[202:203], v[230:231]
	v_cvt_pk_f32_fp8_sdwa v[232:233], v50 src0_sel:WORD_1
	v_pk_fma_f32 v[230:231], v[234:235], v[204:205], v[230:231]
	v_cvt_pk_f32_fp8_e32 v[234:235], v51
	v_pk_fma_f32 v[230:231], v[236:237], v[206:207], v[230:231]
	v_cvt_pk_f32_fp8_sdwa v[236:237], v51 src0_sel:WORD_1
	v_pk_fma_f32 v[230:231], v[238:239], v[208:209], v[230:231]
	v_cvt_pk_f32_fp8_sdwa v[238:239], v53 src0_sel:WORD_1
	v_add_f32_e32 v189, v230, v231
	v_cvt_pk_f32_fp8_e32 v[230:231], v50
	v_pk_fma_f32 v[230:231], v[230:231], v[210:211], 0 op_sel_hi:[1,1,0]
	s_nop 0
	v_pk_fma_f32 v[230:231], v[232:233], v[212:213], v[230:231]
	v_cvt_pk_f32_fp8_e32 v[232:233], v52
	v_pk_fma_f32 v[230:231], v[234:235], v[214:215], v[230:231]
	v_cvt_pk_f32_fp8_sdwa v[234:235], v52 src0_sel:WORD_1
	v_pk_fma_f32 v[230:231], v[236:237], v[216:217], v[230:231]
	v_cvt_pk_f32_fp8_e32 v[236:237], v53
	v_pk_fma_f32 v[230:231], v[232:233], v[202:203], v[230:231]
	v_cvt_pk_f32_fp8_sdwa v[232:233], v54 src0_sel:WORD_1
	v_pk_fma_f32 v[230:231], v[234:235], v[204:205], v[230:231]
	v_cvt_pk_f32_fp8_e32 v[234:235], v55
	v_pk_fma_f32 v[230:231], v[236:237], v[206:207], v[230:231]
	v_cvt_pk_f32_fp8_sdwa v[236:237], v55 src0_sel:WORD_1
	v_pk_fma_f32 v[230:231], v[238:239], v[208:209], v[230:231]
	v_cvt_pk_f32_fp8_sdwa v[238:239], v57 src0_sel:WORD_1
	v_add_f32_e32 v229, v230, v231
	v_cvt_pk_f32_fp8_e32 v[230:231], v54
	v_pk_fma_f32 v[230:231], v[230:231], v[210:211], 0 op_sel_hi:[1,1,0]
	s_nop 0
	v_pk_fma_f32 v[230:231], v[232:233], v[212:213], v[230:231]
	v_cvt_pk_f32_fp8_e32 v[232:233], v56
	v_pk_fma_f32 v[230:231], v[234:235], v[214:215], v[230:231]
	v_cvt_pk_f32_fp8_sdwa v[234:235], v56 src0_sel:WORD_1
	v_pk_fma_f32 v[230:231], v[236:237], v[216:217], v[230:231]
	v_cvt_pk_f32_fp8_e32 v[236:237], v57
	v_pk_fma_f32 v[230:231], v[232:233], v[202:203], v[230:231]
	v_cvt_pk_f32_fp8_sdwa v[232:233], v58 src0_sel:WORD_1
	v_pk_fma_f32 v[230:231], v[234:235], v[204:205], v[230:231]
	v_cvt_pk_f32_fp8_e32 v[234:235], v59
	v_pk_fma_f32 v[230:231], v[236:237], v[206:207], v[230:231]
	v_cvt_pk_f32_fp8_sdwa v[236:237], v59 src0_sel:WORD_1
	v_pk_fma_f32 v[230:231], v[238:239], v[208:209], v[230:231]
	v_cvt_pk_f32_fp8_sdwa v[238:239], v61 src0_sel:WORD_1
	v_add_f32_e32 v240, v230, v231
	v_cvt_pk_f32_fp8_e32 v[230:231], v58
	v_pk_fma_f32 v[230:231], v[230:231], v[210:211], 0 op_sel_hi:[1,1,0]
	s_nop 0
	v_pk_fma_f32 v[230:231], v[232:233], v[212:213], v[230:231]
	v_cvt_pk_f32_fp8_e32 v[232:233], v60
	v_pk_fma_f32 v[230:231], v[234:235], v[214:215], v[230:231]
	v_cvt_pk_f32_fp8_sdwa v[234:235], v60 src0_sel:WORD_1
	v_pk_fma_f32 v[230:231], v[236:237], v[216:217], v[230:231]
	v_cvt_pk_f32_fp8_e32 v[236:237], v61
	v_pk_fma_f32 v[230:231], v[232:233], v[202:203], v[230:231]
	v_cvt_pk_f32_fp8_sdwa v[232:233], v62 src0_sel:WORD_1
	v_pk_fma_f32 v[230:231], v[234:235], v[204:205], v[230:231]
	v_cvt_pk_f32_fp8_e32 v[234:235], v63
	v_pk_fma_f32 v[230:231], v[236:237], v[206:207], v[230:231]
	v_cvt_pk_f32_fp8_sdwa v[236:237], v63 src0_sel:WORD_1
	v_pk_fma_f32 v[230:231], v[238:239], v[208:209], v[230:231]
	s_nop 0
	v_add_f32_e32 v238, v230, v231
	v_cvt_pk_f32_fp8_e32 v[230:231], v62
	v_pk_fma_f32 v[210:211], v[230:231], v[210:211], 0 op_sel_hi:[1,1,0]
; DI void dn2_math(const u32x4 (&W)[16], u32x4 x0, u32x4 x1, float* __restrict__ parow, int lane) {
;     ...
;   const bool b2 = lane & 4, b1 = lane & 2, b0 = lane & 1;
;   float q8[8];
; #pragma unroll
;   for (int i = 0; i < 8; ++i) { float snd = b2 ? pv[i] : pv[i + 8]; float kp = b2 ? pv[i + 8] : pv[i]; q8[i] = kp + __shfl_xor(snd, 4); }
;   float q4[4];
; #pragma unroll
;   for (int i = 0; i < 4; ++i) { float snd = b1 ? q8[i] : q8[i + 4]; float kp = b1 ? q8[i + 4] : q8[i]; q4[i] = kp + __shfl_xor(snd, 2); }
;   float r2[2];
; #pragma unroll
;   for (int i = 0; i < 2; ++i) { float snd = b0 ? q4[i] : q4[i + 2]; float kp = b0 ? q4[i + 2] : q4[i]; r2[i] = kp + __shfl_xor(snd, 1); }
;   const int j0 = (b0 ? 2 : 0) + (b1 ? 4 : 0) + (b2 ? 8 : 0);
;   const int grp = lane >> 3;
;   parow[8 * j0 + grp] = r2[0];
;   parow[8 * (j0 + 1) + grp] = r2[1];
; DI void peer_down2_phase(const Params& p, unsigned char* smem, int layer, const bf16* __restrict__ x1b, u32* ctr) {
;     ...
;         if (tl + 2 < 16) {
;           dn2_issue(WA, pl + (tl + 2) * 128, wbase, grp);
;           xa0 = *(const u32x4*)(xb0 + (size_t)(tl + 2) * 1024); xa1 = *(const u32x4*)(xb0 + (size_t)(tl + 2) * 1024 + 8);
;         }
	s_nop 0
	v_pk_fma_f32 v[210:211], v[232:233], v[212:213], v[210:211]
	v_cvt_pk_f32_fp8_e32 v[212:213], v64
	v_pk_fma_f32 v[210:211], v[234:235], v[214:215], v[210:211]
	v_cvt_pk_f32_fp8_sdwa v[214:215], v64 src0_sel:WORD_1
	v_pk_fma_f32 v[210:211], v[236:237], v[216:217], v[210:211]
	v_cvt_pk_f32_fp8_e32 v[216:217], v65
	v_cvt_pk_f32_fp8_sdwa v[230:231], v65 src0_sel:WORD_1
	v_pk_fma_f32 v[202:203], v[212:213], v[202:203], v[210:211]
	s_nop 0
	v_pk_fma_f32 v[202:203], v[214:215], v[204:205], v[202:203]
	v_pk_fma_f32 v[202:203], v[216:217], v[206:207], v[202:203]
	v_pk_fma_f32 v[202:203], v[230:231], v[208:209], v[202:203]
	v_add_f32_e32 v202, v202, v203
	s_nop 1
	v_add_f32_dpp v167, v167, v167 row_shl:4 row_mask:0xf bank_mask:0x5
	v_add_f32_dpp v173, v173, v173 row_shl:4 row_mask:0xf bank_mask:0x5
	v_add_f32_dpp v175, v175, v175 row_shl:4 row_mask:0xf bank_mask:0x5
	v_add_f32_dpp v169, v169, v169 row_shl:4 row_mask:0xf bank_mask:0x5
	v_add_f32_dpp v171, v171, v171 row_shl:4 row_mask:0xf bank_mask:0x5
	v_add_f32_dpp v177, v177, v177 row_shl:4 row_mask:0xf bank_mask:0x5
	v_add_f32_dpp v179, v179, v179 row_shl:4 row_mask:0xf bank_mask:0x5
	v_add_f32_dpp v181, v181, v181 row_shl:4 row_mask:0xf bank_mask:0x5
	v_add_f32_dpp v167, v183, v183 row_shr:4 row_mask:0xf bank_mask:0xa
	v_add_f32_dpp v173, v189, v189 row_shr:4 row_mask:0xf bank_mask:0xa
	v_add_f32_dpp v175, v229, v229 row_shr:4 row_mask:0xf bank_mask:0xa
	v_add_f32_dpp v169, v185, v185 row_shr:4 row_mask:0xf bank_mask:0xa
	v_add_f32_dpp v171, v187, v187 row_shr:4 row_mask:0xf bank_mask:0xa
	v_add_f32_dpp v177, v240, v240 row_shr:4 row_mask:0xf bank_mask:0xa
	v_add_f32_dpp v179, v238, v238 row_shr:4 row_mask:0xf bank_mask:0xa
	v_add_f32_dpp v181, v202, v202 row_shr:4 row_mask:0xf bank_mask:0xa
	s_nop 1
	v_add_f32_dpp v167, v167, v167 quad_perm:[2,3,0,1] row_mask:0xf bank_mask:0xf
	v_add_f32_dpp v171, v171, v171 quad_perm:[2,3,0,1] row_mask:0xf bank_mask:0xf
	v_add_f32_dpp v169, v169, v169 quad_perm:[2,3,0,1] row_mask:0xf bank_mask:0xf
	v_add_f32_dpp v173, v173, v173 quad_perm:[2,3,0,1] row_mask:0xf bank_mask:0xf
	v_add_f32_dpp v175, v175, v175 quad_perm:[2,3,0,1] row_mask:0xf bank_mask:0xf
	v_add_f32_dpp v179, v179, v179 quad_perm:[2,3,0,1] row_mask:0xf bank_mask:0xf
	v_add_f32_dpp v177, v177, v177 quad_perm:[2,3,0,1] row_mask:0xf bank_mask:0xf
	v_add_f32_dpp v181, v181, v181 quad_perm:[2,3,0,1] row_mask:0xf bank_mask:0xf
	v_cndmask_b32_e64 v167, v175, v167, s[10:11]
	v_cndmask_b32_e64 v171, v179, v171, s[10:11]
	v_cndmask_b32_e64 v169, v177, v169, s[10:11]
	v_cndmask_b32_e64 v173, v181, v173, s[10:11]
	s_nop 1
	v_add_f32_dpp v167, v167, v167 quad_perm:[1,0,3,2] row_mask:0xf bank_mask:0xf
	v_add_f32_dpp v169, v169, v169 quad_perm:[1,0,3,2] row_mask:0xf bank_mask:0xf
	v_add_f32_dpp v171, v171, v171 quad_perm:[1,0,3,2] row_mask:0xf bank_mask:0xf
	v_add_f32_dpp v173, v173, v173 quad_perm:[1,0,3,2] row_mask:0xf bank_mask:0xf
	v_cndmask_b32_e64 v167, v171, v167, s[12:13]
	v_cndmask_b32_e64 v169, v173, v169, s[12:13]
	global_store_dword v[200:201], v167, off offset:-512
	global_store_dword v[200:201], v169, off offset:-480
	s_cmp_gt_u32 s40, 13
	s_cselect_b64 s[28:29], -1, 0
	s_and_b64 vcc, exec, s[28:29]
	s_cbranch_vccnz .LBB0_1516
	ds_read2_b32 v[2:3], v165 offset0:128 offset1:136
	ds_read2_b32 v[10:11], v165 offset0:144 offset1:152
	ds_read2_b32 v[18:19], v165 offset0:160 offset1:168
	ds_read2_b32 v[26:27], v165 offset0:176 offset1:184
	ds_read2_b32 v[34:35], v165 offset0:192 offset1:200
	ds_read2_b32 v[42:43], v165 offset0:208 offset1:216
	ds_read2_b32 v[50:51], v165 offset0:224 offset1:232
	ds_read2_b32 v[58:59], v165 offset0:240 offset1:248
	s_waitcnt lgkmcnt(7)
	v_lshl_add_u32 v6, v3, 10, v250
	v_lshl_add_u32 v2, v2, 10, v250
	global_load_dwordx4 v[2:5], v2, s[98:99]
	global_load_dwordx4 v[6:9], v6, s[98:99]
	s_waitcnt lgkmcnt(6)
	v_lshl_add_u32 v14, v11, 10, v250
	v_lshl_add_u32 v10, v10, 10, v250
	global_load_dwordx4 v[10:13], v10, s[98:99]
	global_load_dwordx4 v[14:17], v14, s[98:99]
	s_waitcnt lgkmcnt(5)
	v_lshl_add_u32 v22, v19, 10, v250
	v_lshl_add_u32 v18, v18, 10, v250
	global_load_dwordx4 v[18:21], v18, s[98:99]
	global_load_dwordx4 v[22:25], v22, s[98:99]
	s_waitcnt lgkmcnt(4)
	v_lshl_add_u32 v30, v27, 10, v250
	v_lshl_add_u32 v26, v26, 10, v250
	global_load_dwordx4 v[26:29], v26, s[98:99]
	global_load_dwordx4 v[30:33], v30, s[98:99]
	s_waitcnt lgkmcnt(3)
	v_lshl_add_u32 v38, v35, 10, v250
	v_lshl_add_u32 v34, v34, 10, v250
	global_load_dwordx4 v[34:37], v34, s[98:99]
	global_load_dwordx4 v[38:41], v38, s[98:99]
	s_waitcnt lgkmcnt(2)
	v_lshl_add_u32 v46, v43, 10, v250
	v_lshl_add_u32 v42, v42, 10, v250
	global_load_dwordx4 v[42:45], v42, s[98:99]
	global_load_dwordx4 v[46:49], v46, s[98:99]
	s_waitcnt lgkmcnt(1)
	v_lshl_add_u32 v54, v51, 10, v250
	v_lshl_add_u32 v50, v50, 10, v250
	global_load_dwordx4 v[50:53], v50, s[98:99]
	global_load_dwordx4 v[54:57], v54, s[98:99]
	s_waitcnt lgkmcnt(0)
	v_lshl_add_u32 v62, v59, 10, v250
	v_lshl_add_u32 v58, v58, 10, v250
	global_load_dwordx4 v[58:61], v58, s[98:99]
	global_load_dwordx4 v[62:65], v62, s[98:99]
	s_nop 0
	global_load_dwordx4 v[66:69], v[198:199], off offset:16
	global_load_dwordx4 v[70:73], v[198:199], off
	s_branch .LBB0_1516
